# static priority: the per-phase s_setprio 1/0 flips around the 16-MFMA clusters of the three 8-phase GEMM main loops deleted (all waves stay at priority 0)
# speedup vs baseline: 1.0212x; 1.0080x over previous
.LBB0_212:
	s_add_u32 s28, s12, s18
	ds_read_b128 v[150:153], v140
	ds_read_b128 v[154:157], v140 offset:1024
	ds_read_b128 v[158:161], v140 offset:2048
	ds_read_b128 v[162:165], v140 offset:3072
	s_addc_u32 s29, s13, s19
	s_add_u32 s28, s28, 0x100
	s_addc_u32 s29, s29, 0
	s_add_u32 s33, s60, s18
	s_addc_u32 s85, s61, s19
	s_cmpk_eq_i32 s18, 0x700
	s_cselect_b32 s37, s13, s29
	s_cselect_b32 s36, s12, s28
	s_cselect_b32 s29, s11, s85
	s_cselect_b32 s28, s10, s33
	s_mov_b32 m0, s63
	v_lshl_add_u64 v[146:147], v[136:137], 0, s[18:19]
	ds_read_b128 v[166:169], v141
	ds_read_b128 v[170:173], v141 offset:1024
	ds_read_b128 v[174:177], v141 offset:2048
	ds_read_b128 v[178:181], v141 offset:3072
	ds_read_b128 v[182:185], v141 offset:4096
	ds_read_b128 v[186:189], v141 offset:5120
	ds_read_b128 v[190:193], v141 offset:6144
	ds_read_b128 v[194:197], v141 offset:7168
	global_load_lds_dwordx4 v[146:147], off
	v_lshl_add_u64 v[146:147], v[138:139], 0, s[18:19]
	s_mov_b32 m0, s64
	s_nop 0
	global_load_lds_dwordx4 v[146:147], off
	s_waitcnt lgkmcnt(8)
	s_barrier
	s_waitcnt lgkmcnt(0)
	s_waitcnt lgkmcnt(0)
	v_mfma_f32_16x16x32_bf16 v[124:127], v[150:153], v[166:169], v[124:127]
	v_mfma_f32_16x16x32_bf16 v[92:95], v[158:161], v[166:169], v[92:95]
	v_mfma_f32_16x16x32_bf16 v[120:123], v[150:153], v[174:177], v[120:123]
	v_mfma_f32_16x16x32_bf16 v[88:91], v[158:161], v[174:177], v[88:91]
	v_mfma_f32_16x16x32_bf16 v[116:119], v[150:153], v[182:185], v[116:119]
	v_mfma_f32_16x16x32_bf16 v[84:87], v[158:161], v[182:185], v[84:87]
	v_mfma_f32_16x16x32_bf16 v[112:115], v[150:153], v[190:193], v[112:115]
	v_mfma_f32_16x16x32_bf16 v[80:83], v[158:161], v[190:193], v[80:83]
	v_mfma_f32_16x16x32_bf16 v[124:127], v[154:157], v[170:173], v[124:127]
	v_mfma_f32_16x16x32_bf16 v[92:95], v[162:165], v[170:173], v[92:95]
	v_mfma_f32_16x16x32_bf16 v[120:123], v[154:157], v[178:181], v[120:123]
	v_mfma_f32_16x16x32_bf16 v[88:91], v[162:165], v[178:181], v[88:91]
	v_mfma_f32_16x16x32_bf16 v[116:119], v[154:157], v[186:189], v[116:119]
	v_mfma_f32_16x16x32_bf16 v[84:87], v[162:165], v[186:189], v[84:87]
	v_mfma_f32_16x16x32_bf16 v[112:115], v[154:157], v[194:197], v[112:115]
	v_mfma_f32_16x16x32_bf16 v[80:83], v[162:165], v[194:197], v[80:83]
	s_barrier
	s_mov_b32 m0, s65
	v_lshl_add_u64 v[146:147], s[28:29], 0, v[130:131]
	ds_read_b128 v[198:201], v142
	ds_read_b128 v[202:205], v142 offset:1024
	ds_read_b128 v[206:209], v142 offset:2048
	ds_read_b128 v[210:213], v142 offset:3072
	global_load_lds_dwordx4 v[146:147], off
	v_lshl_add_u64 v[214:215], s[28:29], 0, v[134:135]
	s_mov_b32 m0, s66
	s_nop 0
	global_load_lds_dwordx4 v[214:215], off
	s_barrier
	s_waitcnt lgkmcnt(0)
	s_waitcnt lgkmcnt(0)
	v_mfma_f32_16x16x32_bf16 v[60:63], v[198:201], v[166:169], v[60:63]
	v_mfma_f32_16x16x32_bf16 v[28:31], v[206:209], v[166:169], v[28:31]
	v_mfma_f32_16x16x32_bf16 v[56:59], v[198:201], v[174:177], v[56:59]
	v_mfma_f32_16x16x32_bf16 v[24:27], v[206:209], v[174:177], v[24:27]
	v_mfma_f32_16x16x32_bf16 v[52:55], v[198:201], v[182:185], v[52:55]
	v_mfma_f32_16x16x32_bf16 v[20:23], v[206:209], v[182:185], v[20:23]
	v_mfma_f32_16x16x32_bf16 v[48:51], v[198:201], v[190:193], v[48:51]
	v_mfma_f32_16x16x32_bf16 v[16:19], v[206:209], v[190:193], v[16:19]
	v_mfma_f32_16x16x32_bf16 v[60:63], v[202:205], v[170:173], v[60:63]
	v_mfma_f32_16x16x32_bf16 v[28:31], v[210:213], v[170:173], v[28:31]
	v_mfma_f32_16x16x32_bf16 v[56:59], v[202:205], v[178:181], v[56:59]
	v_mfma_f32_16x16x32_bf16 v[24:27], v[210:213], v[178:181], v[24:27]
	v_mfma_f32_16x16x32_bf16 v[52:55], v[202:205], v[186:189], v[52:55]
	v_mfma_f32_16x16x32_bf16 v[20:23], v[210:213], v[186:189], v[20:23]
	v_mfma_f32_16x16x32_bf16 v[48:51], v[202:205], v[194:197], v[48:51]
	v_mfma_f32_16x16x32_bf16 v[16:19], v[210:213], v[194:197], v[16:19]
	s_mov_b32 m0, s5
	v_lshl_add_u64 v[218:219], s[36:37], 0, v[128:129]
	s_barrier
	ds_read_b128 v[166:169], v141 offset:16384
	ds_read_b128 v[170:173], v141 offset:17408
	ds_read_b128 v[174:177], v141 offset:18432
	ds_read_b128 v[178:181], v141 offset:19456
	ds_read_b128 v[182:185], v141 offset:20480
	ds_read_b128 v[186:189], v141 offset:21504
	ds_read_b128 v[190:193], v141 offset:22528
	ds_read_b128 v[194:197], v141 offset:23552
	global_load_lds_dwordx4 v[218:219], off
	v_lshl_add_u64 v[220:221], s[36:37], 0, v[132:133]
	s_mov_b32 m0, s54
	s_nop 0
	global_load_lds_dwordx4 v[220:221], off
	s_barrier
	s_waitcnt lgkmcnt(0)
	s_waitcnt lgkmcnt(0)
	v_mfma_f32_16x16x32_bf16 v[108:111], v[150:153], v[166:169], v[108:111]
	v_mfma_f32_16x16x32_bf16 v[76:79], v[158:161], v[166:169], v[76:79]
	v_mfma_f32_16x16x32_bf16 v[104:107], v[150:153], v[174:177], v[104:107]
	v_mfma_f32_16x16x32_bf16 v[72:75], v[158:161], v[174:177], v[72:75]
	v_mfma_f32_16x16x32_bf16 v[100:103], v[150:153], v[182:185], v[100:103]
	v_mfma_f32_16x16x32_bf16 v[68:71], v[158:161], v[182:185], v[68:71]
	v_mfma_f32_16x16x32_bf16 v[96:99], v[150:153], v[190:193], v[96:99]
	v_mfma_f32_16x16x32_bf16 v[64:67], v[158:161], v[190:193], v[64:67]
	v_mfma_f32_16x16x32_bf16 v[108:111], v[154:157], v[170:173], v[108:111]
	v_mfma_f32_16x16x32_bf16 v[76:79], v[162:165], v[170:173], v[76:79]
	v_mfma_f32_16x16x32_bf16 v[104:107], v[154:157], v[178:181], v[104:107]
	v_mfma_f32_16x16x32_bf16 v[72:75], v[162:165], v[178:181], v[72:75]
	v_mfma_f32_16x16x32_bf16 v[100:103], v[154:157], v[186:189], v[100:103]
	v_mfma_f32_16x16x32_bf16 v[68:71], v[162:165], v[186:189], v[68:71]
	v_mfma_f32_16x16x32_bf16 v[96:99], v[154:157], v[194:197], v[96:99]
	v_mfma_f32_16x16x32_bf16 v[64:67], v[162:165], v[194:197], v[64:67]
	s_barrier
	s_add_u32 s86, s28, 0x40000
	s_addc_u32 s87, s29, 0
	s_mov_b32 m0, s67
	v_lshl_add_u64 v[150:151], s[86:87], 0, v[130:131]
	global_load_lds_dwordx4 v[150:151], off
	v_lshl_add_u64 v[150:151], s[86:87], 0, v[134:135]
	s_mov_b32 m0, s80
	s_nop 0
	global_load_lds_dwordx4 v[150:151], off
	s_waitcnt vmcnt(6)
	s_barrier
	v_mfma_f32_16x16x32_bf16 v[44:47], v[198:201], v[166:169], v[44:47]
	v_mfma_f32_16x16x32_bf16 v[12:15], v[206:209], v[166:169], v[12:15]
	v_mfma_f32_16x16x32_bf16 v[40:43], v[198:201], v[174:177], v[40:43]
	v_mfma_f32_16x16x32_bf16 v[8:11], v[206:209], v[174:177], v[8:11]
	v_mfma_f32_16x16x32_bf16 v[36:39], v[198:201], v[182:185], v[36:39]
	v_mfma_f32_16x16x32_bf16 v[4:7], v[206:209], v[182:185], v[4:7]
	v_mfma_f32_16x16x32_bf16 v[32:35], v[198:201], v[190:193], v[32:35]
	v_mfma_f32_16x16x32_bf16 v[0:3], v[206:209], v[190:193], v[0:3]
	v_mfma_f32_16x16x32_bf16 v[44:47], v[202:205], v[170:173], v[44:47]
	v_mfma_f32_16x16x32_bf16 v[12:15], v[210:213], v[170:173], v[12:15]
	v_mfma_f32_16x16x32_bf16 v[40:43], v[202:205], v[178:181], v[40:43]
	v_mfma_f32_16x16x32_bf16 v[8:11], v[210:213], v[178:181], v[8:11]
	v_mfma_f32_16x16x32_bf16 v[36:39], v[202:205], v[186:189], v[36:39]
	v_mfma_f32_16x16x32_bf16 v[4:7], v[210:213], v[186:189], v[4:7]
	v_mfma_f32_16x16x32_bf16 v[32:35], v[202:205], v[194:197], v[32:35]
	v_mfma_f32_16x16x32_bf16 v[0:3], v[210:213], v[194:197], v[0:3]
	s_barrier
	ds_read_b128 v[150:153], v143
	ds_read_b128 v[154:157], v143 offset:1024
	ds_read_b128 v[158:161], v143 offset:2048
	ds_read_b128 v[162:165], v143 offset:3072
	s_add_u32 s36, s36, 0x40000
	s_addc_u32 s37, s37, 0
	s_mov_b32 m0, s56
	v_lshl_add_u64 v[198:199], s[36:37], 0, v[128:129]
	ds_read_b128 v[166:169], v141 offset:32768
	ds_read_b128 v[170:173], v141 offset:33792
	ds_read_b128 v[174:177], v141 offset:34816
	ds_read_b128 v[178:181], v141 offset:35840
	ds_read_b128 v[182:185], v141 offset:36864
	ds_read_b128 v[186:189], v141 offset:37888
	ds_read_b128 v[190:193], v141 offset:38912
	ds_read_b128 v[194:197], v141 offset:39936
	global_load_lds_dwordx4 v[198:199], off
	v_lshl_add_u64 v[198:199], s[36:37], 0, v[132:133]
	s_mov_b32 m0, s57
	s_nop 0
	global_load_lds_dwordx4 v[198:199], off
	s_waitcnt lgkmcnt(8)
	s_barrier
	s_waitcnt lgkmcnt(0)
	s_waitcnt lgkmcnt(0)
	v_mfma_f32_16x16x32_bf16 v[124:127], v[150:153], v[166:169], v[124:127]
	v_mfma_f32_16x16x32_bf16 v[92:95], v[158:161], v[166:169], v[92:95]
	v_mfma_f32_16x16x32_bf16 v[120:123], v[150:153], v[174:177], v[120:123]
	v_mfma_f32_16x16x32_bf16 v[88:91], v[158:161], v[174:177], v[88:91]
	v_mfma_f32_16x16x32_bf16 v[116:119], v[150:153], v[182:185], v[116:119]
	v_mfma_f32_16x16x32_bf16 v[84:87], v[158:161], v[182:185], v[84:87]
	v_mfma_f32_16x16x32_bf16 v[112:115], v[150:153], v[190:193], v[112:115]
	v_mfma_f32_16x16x32_bf16 v[80:83], v[158:161], v[190:193], v[80:83]
	v_mfma_f32_16x16x32_bf16 v[124:127], v[154:157], v[170:173], v[124:127]
	v_mfma_f32_16x16x32_bf16 v[92:95], v[162:165], v[170:173], v[92:95]
	v_mfma_f32_16x16x32_bf16 v[120:123], v[154:157], v[178:181], v[120:123]
	v_mfma_f32_16x16x32_bf16 v[88:91], v[162:165], v[178:181], v[88:91]
	v_mfma_f32_16x16x32_bf16 v[116:119], v[154:157], v[186:189], v[116:119]
	v_mfma_f32_16x16x32_bf16 v[84:87], v[162:165], v[186:189], v[84:87]
	v_mfma_f32_16x16x32_bf16 v[112:115], v[154:157], v[194:197], v[112:115]
	v_mfma_f32_16x16x32_bf16 v[80:83], v[162:165], v[194:197], v[80:83]
	s_barrier
	s_mov_b32 m0, s81
	v_lshl_add_u64 v[146:147], v[146:147], 0, s[14:15]
	ds_read_b128 v[198:201], v145
	ds_read_b128 v[202:205], v145 offset:1024
	ds_read_b128 v[206:209], v145 offset:2048
	ds_read_b128 v[210:213], v145 offset:3072
	global_load_lds_dwordx4 v[146:147], off
	v_lshl_add_u64 v[146:147], v[214:215], 0, s[14:15]
	s_mov_b32 m0, s82
	s_nop 0
	global_load_lds_dwordx4 v[146:147], off
	s_barrier
	s_waitcnt lgkmcnt(0)
	s_waitcnt lgkmcnt(0)
	v_mfma_f32_16x16x32_bf16 v[60:63], v[198:201], v[166:169], v[60:63]
	v_mfma_f32_16x16x32_bf16 v[28:31], v[206:209], v[166:169], v[28:31]
	v_mfma_f32_16x16x32_bf16 v[56:59], v[198:201], v[174:177], v[56:59]
	v_mfma_f32_16x16x32_bf16 v[24:27], v[206:209], v[174:177], v[24:27]
	v_mfma_f32_16x16x32_bf16 v[52:55], v[198:201], v[182:185], v[52:55]
	v_mfma_f32_16x16x32_bf16 v[20:23], v[206:209], v[182:185], v[20:23]
	v_mfma_f32_16x16x32_bf16 v[48:51], v[198:201], v[190:193], v[48:51]
	v_mfma_f32_16x16x32_bf16 v[16:19], v[206:209], v[190:193], v[16:19]
	v_mfma_f32_16x16x32_bf16 v[60:63], v[202:205], v[170:173], v[60:63]
	v_mfma_f32_16x16x32_bf16 v[28:31], v[210:213], v[170:173], v[28:31]
	v_mfma_f32_16x16x32_bf16 v[56:59], v[202:205], v[178:181], v[56:59]
	v_mfma_f32_16x16x32_bf16 v[24:27], v[210:213], v[178:181], v[24:27]
	v_mfma_f32_16x16x32_bf16 v[52:55], v[202:205], v[186:189], v[52:55]
	v_mfma_f32_16x16x32_bf16 v[20:23], v[210:213], v[186:189], v[20:23]
	v_mfma_f32_16x16x32_bf16 v[48:51], v[202:205], v[194:197], v[48:51]
	v_mfma_f32_16x16x32_bf16 v[16:19], v[210:213], v[194:197], v[16:19]
	s_mov_b32 m0, s58
	v_lshl_add_u64 v[146:147], v[218:219], 0, s[14:15]
	s_barrier
	ds_read_b128 v[166:169], v141 offset:49152
	ds_read_b128 v[170:173], v141 offset:50176
	ds_read_b128 v[174:177], v141 offset:51200
	ds_read_b128 v[178:181], v141 offset:52224
	ds_read_b128 v[182:185], v141 offset:53248
	ds_read_b128 v[186:189], v141 offset:54272
	ds_read_b128 v[190:193], v141 offset:55296
	ds_read_b128 v[194:197], v141 offset:56320
	global_load_lds_dwordx4 v[146:147], off
	v_lshl_add_u64 v[146:147], v[220:221], 0, s[14:15]
	s_mov_b32 m0, s59
	s_nop 0
	global_load_lds_dwordx4 v[146:147], off
	s_barrier
	s_waitcnt lgkmcnt(0)
	s_waitcnt lgkmcnt(0)
	v_mfma_f32_16x16x32_bf16 v[108:111], v[150:153], v[166:169], v[108:111]
	v_mfma_f32_16x16x32_bf16 v[76:79], v[158:161], v[166:169], v[76:79]
	v_mfma_f32_16x16x32_bf16 v[104:107], v[150:153], v[174:177], v[104:107]
	v_mfma_f32_16x16x32_bf16 v[72:75], v[158:161], v[174:177], v[72:75]
	v_mfma_f32_16x16x32_bf16 v[100:103], v[150:153], v[182:185], v[100:103]
	v_mfma_f32_16x16x32_bf16 v[68:71], v[158:161], v[182:185], v[68:71]
	v_mfma_f32_16x16x32_bf16 v[96:99], v[150:153], v[190:193], v[96:99]
	v_mfma_f32_16x16x32_bf16 v[64:67], v[158:161], v[190:193], v[64:67]
	v_mfma_f32_16x16x32_bf16 v[108:111], v[154:157], v[170:173], v[108:111]
	v_mfma_f32_16x16x32_bf16 v[76:79], v[162:165], v[170:173], v[76:79]
	v_mfma_f32_16x16x32_bf16 v[104:107], v[154:157], v[178:181], v[104:107]
	v_mfma_f32_16x16x32_bf16 v[72:75], v[162:165], v[178:181], v[72:75]
	v_mfma_f32_16x16x32_bf16 v[100:103], v[154:157], v[186:189], v[100:103]
	v_mfma_f32_16x16x32_bf16 v[68:71], v[162:165], v[186:189], v[68:71]
	v_mfma_f32_16x16x32_bf16 v[96:99], v[154:157], v[194:197], v[96:99]
	v_mfma_f32_16x16x32_bf16 v[64:67], v[162:165], v[194:197], v[64:67]
	s_barrier
	s_add_u32 s28, s28, 0x40080
	s_addc_u32 s29, s29, 0
	s_mov_b32 m0, s83
	v_lshl_add_u64 v[146:147], s[28:29], 0, v[130:131]
	global_load_lds_dwordx4 v[146:147], off
	v_lshl_add_u64 v[146:147], s[28:29], 0, v[134:135]
	s_mov_b32 m0, s84
	s_nop 0
	global_load_lds_dwordx4 v[146:147], off
	s_waitcnt vmcnt(6)
	s_barrier
	v_mfma_f32_16x16x32_bf16 v[44:47], v[198:201], v[166:169], v[44:47]
	v_mfma_f32_16x16x32_bf16 v[12:15], v[206:209], v[166:169], v[12:15]
	v_mfma_f32_16x16x32_bf16 v[40:43], v[198:201], v[174:177], v[40:43]
	v_mfma_f32_16x16x32_bf16 v[8:11], v[206:209], v[174:177], v[8:11]
	v_mfma_f32_16x16x32_bf16 v[36:39], v[198:201], v[182:185], v[36:39]
	v_mfma_f32_16x16x32_bf16 v[4:7], v[206:209], v[182:185], v[4:7]
	v_mfma_f32_16x16x32_bf16 v[32:35], v[198:201], v[190:193], v[32:35]
	v_mfma_f32_16x16x32_bf16 v[0:3], v[206:209], v[190:193], v[0:3]
	v_mfma_f32_16x16x32_bf16 v[44:47], v[202:205], v[170:173], v[44:47]
	v_mfma_f32_16x16x32_bf16 v[12:15], v[210:213], v[170:173], v[12:15]
	v_mfma_f32_16x16x32_bf16 v[40:43], v[202:205], v[178:181], v[40:43]
	v_mfma_f32_16x16x32_bf16 v[8:11], v[210:213], v[178:181], v[8:11]
	v_mfma_f32_16x16x32_bf16 v[36:39], v[202:205], v[186:189], v[36:39]
	v_mfma_f32_16x16x32_bf16 v[4:7], v[210:213], v[186:189], v[4:7]
	v_mfma_f32_16x16x32_bf16 v[32:35], v[202:205], v[194:197], v[32:35]
	v_mfma_f32_16x16x32_bf16 v[0:3], v[210:213], v[194:197], v[0:3]
	s_add_i32 s62, s62, 2
	s_add_u32 s18, s18, 0x100
	s_addc_u32 s19, s19, 0
	s_cmp_gt_u32 s62, 13
	s_barrier
	s_cbranch_scc0 .LBB0_212
	s_and_b32 s5, s2, 1
	s_and_b32 s4, s4, 10
	s_cmp_lg_u32 s4, 10
	s_mov_b64 s[10:11], -1
	s_cbranch_scc0 .LBB0_215
	v_lshlrev_b32_e32 v128, 2, v148
	global_load_dwordx4 v[140:143], v128, s[24:25]
	global_load_dwordx4 v[136:139], v128, s[24:25] offset:16
	global_load_dwordx4 v[132:135], v128, s[24:25] offset:128
	s_nop 0
	global_load_dwordx4 v[128:131], v128, s[24:25] offset:144
	v_mul_f32_e32 v146, v125, v125
	v_mul_f32_e32 v150, v127, v127
	v_mul_f32_e32 v151, v93, v93
	v_mul_f32_e32 v152, v95, v95
	v_mul_f32_e32 v153, v61, v61
	v_mul_f32_e32 v154, v63, v63
	v_fmac_f32_e32 v146, v124, v124
	v_fmac_f32_e32 v150, v126, v126
	v_fmac_f32_e32 v151, v92, v92
	v_fmac_f32_e32 v152, v94, v94
	v_mul_f32_e32 v155, v29, v29
	v_mul_f32_e32 v156, v31, v31
	v_fmac_f32_e32 v153, v60, v60
	v_fmac_f32_e32 v154, v62, v62
	v_add_f32_e32 v160, v146, v150
	v_add_f32_e32 v152, v151, v152
	v_fmac_f32_e32 v155, v28, v28
	v_fmac_f32_e32 v156, v30, v30
	v_add_f32_e32 v153, v153, v154
	v_add_f32_e32 v152, v160, v152
	v_add_f32_e32 v154, v155, v156
	v_add_f32_e32 v152, v152, v153
	v_add_f32_e32 v152, v152, v154
	v_mov_b32_e32 v153, v152
	s_nop 1
	v_permlane16_swap_b32_e32 v152, v153
	v_add_f32_e32 v152, v152, v153
	v_mov_b32_e32 v153, v152
	s_nop 1
	v_permlane32_swap_b32_e32 v152, v153
	s_load_dwordx8 s[56:63], s[0:1], 0xc0
	s_lshl_b32 s4, s7, 6
	s_lshl_b32 s13, s5, 8
	v_mov_b32_e32 v149, 0x358637bd
	v_add_f32_e32 v152, v152, v153
	s_or_b32 s4, s4, s13
	v_fmamk_f32 v152, v152, 0x3c800000, v149
	v_or_b32_e32 v159, s4, v148
	v_rsq_f32_e32 v152, v152
	s_ashr_i32 s12, s55, 31
	v_mov_b32_e32 v147, 0
	v_lshlrev_b32_e32 v146, 1, v159
	v_bfe_u32 v253, v217, 4, 2
	v_and_b32_e32 v254, 3, v217
	v_sub_u32_e32 v253, v253, v254
	v_lshlrev_b32_e32 v254, 4, v253
	v_sub_u32_e32 v146, v146, v254
	s_lshl_b64 s[10:11], s[8:9], 18
	v_mov_b32_e32 v145, s12
	s_waitcnt lgkmcnt(0)
	v_lshl_add_u64 v[146:147], s[60:61], 0, v[146:147]
	v_mul_f32_e32 v157, v121, v121
	v_mul_f32_e32 v158, v123, v123
	v_add_u32_e32 v254, v144, v253
	v_mov_b32_e32 v255, v145
	v_lshlrev_b64 v[150:151], 10, v[254:255]
	v_lshl_add_u64 v[146:147], v[146:147], 0, s[10:11]
	v_fmac_f32_e32 v157, v120, v120
	v_fmac_f32_e32 v158, v122, v122
	v_lshl_add_u64 v[146:147], v[146:147], 0, v[150:151]
	v_pk_mul_f32 v[150:151], v[124:125], v[152:153] op_sel_hi:[1,0]
	v_mul_f32_e32 v168, v89, v89
	v_mul_f32_e32 v169, v91, v91
	v_add_f32_e32 v145, v157, v158
	v_pk_mul_f32 v[154:155], v[126:127], v[152:153] op_sel_hi:[1,0]
	v_pk_mul_f32 v[156:157], v[92:93], v[152:153] op_sel_hi:[1,0]
	v_pk_mul_f32 v[158:159], v[94:95], v[152:153] op_sel_hi:[1,0]
	v_pk_mul_f32 v[160:161], v[60:61], v[152:153] op_sel_hi:[1,0]
	v_pk_mul_f32 v[162:163], v[62:63], v[152:153] op_sel_hi:[1,0]
	v_pk_mul_f32 v[164:165], v[28:29], v[152:153] op_sel_hi:[1,0]
	v_pk_mul_f32 v[152:153], v[30:31], v[152:153] op_sel_hi:[1,0]
	v_fmac_f32_e32 v168, v88, v88
	v_fmac_f32_e32 v169, v90, v90
	s_movk_i32 s4, 0x4000
	s_mov_b64 s[10:11], 0
	s_waitcnt vmcnt(0)
	v_pk_mul_f32 v[150:151], v[140:141], v[150:151]
	v_pk_mul_f32 v[154:155], v[142:143], v[154:155]
	v_pk_mul_f32 v[156:157], v[136:137], v[156:157]
	v_pk_mul_f32 v[166:167], v[130:131], v[152:153]
	v_cvt_pk_bf16_f32 v150, v150, v151
	v_cvt_pk_bf16_f32 v151, v154, v155
	v_cvt_pk_bf16_f32 v152, v156, v157
	v_pk_mul_f32 v[158:159], v[138:139], v[158:159]
	v_pk_mul_f32 v[162:163], v[134:135], v[162:163]
	v_cvt_pk_bf16_f32 v153, v158, v159
	global_store_dwordx4 v[146:147], v[150:153], off
	v_pk_mul_f32 v[160:161], v[132:133], v[160:161]
	v_pk_mul_f32 v[164:165], v[128:129], v[164:165]
	v_add_f32_e32 v152, v168, v169
	v_add_f32_e32 v145, v145, v152
	v_mul_f32_e32 v152, v57, v57
	v_mul_f32_e32 v153, v59, v59
	v_fmac_f32_e32 v152, v56, v56
	v_fmac_f32_e32 v153, v58, v58
	v_add_f32_e32 v152, v152, v153
	v_add_f32_e32 v145, v145, v152
	v_mul_f32_e32 v152, v25, v25
	v_mul_f32_e32 v153, v27, v27
	v_fmac_f32_e32 v152, v24, v24
	v_fmac_f32_e32 v153, v26, v26
	v_add_f32_e32 v152, v152, v153
	v_add_f32_e32 v145, v145, v152
	v_mov_b32_e32 v152, v145
	s_nop 1
	v_permlane16_swap_b32_e32 v145, v152
	v_add_f32_e32 v145, v145, v152
	v_mov_b32_e32 v152, v145
	s_nop 1
	v_permlane32_swap_b32_e32 v145, v152
	v_add_f32_e32 v145, v145, v152
	v_fmamk_f32 v145, v145, 0x3c800000, v149
	v_rsq_f32_e32 v154, v145
	v_cvt_pk_bf16_f32 v150, v160, v161
	v_cvt_pk_bf16_f32 v151, v162, v163
	v_cvt_pk_bf16_f32 v152, v164, v165
	v_cvt_pk_bf16_f32 v153, v166, v167
	global_store_dwordx4 v[146:147], v[150:153], off offset:64
	v_pk_mul_f32 v[156:157], v[88:89], v[154:155] op_sel_hi:[1,0]
	v_pk_mul_f32 v[158:159], v[90:91], v[154:155] op_sel_hi:[1,0]
	v_pk_mul_f32 v[150:151], v[120:121], v[154:155] op_sel_hi:[1,0]
	v_pk_mul_f32 v[152:153], v[122:123], v[154:155] op_sel_hi:[1,0]
	v_pk_mul_f32 v[150:151], v[140:141], v[150:151]
	v_pk_mul_f32 v[152:153], v[142:143], v[152:153]
	v_pk_mul_f32 v[156:157], v[136:137], v[156:157]
	v_cvt_pk_bf16_f32 v150, v150, v151
	v_cvt_pk_bf16_f32 v151, v152, v153
	v_pk_mul_f32 v[158:159], v[138:139], v[158:159]
	v_cvt_pk_bf16_f32 v152, v156, v157
	v_add_co_u32_e32 v156, vcc, s4, v146
	v_cvt_pk_bf16_f32 v153, v158, v159
	v_mul_f32_e32 v145, v117, v117
	s_nop 0
	v_addc_co_u32_e32 v157, vcc, 0, v147, vcc
	global_store_dwordx4 v[156:157], v[150:153], off
	v_fmac_f32_e32 v145, v116, v116
	v_pk_mul_f32 v[158:159], v[24:25], v[154:155] op_sel_hi:[1,0]
	v_pk_mul_f32 v[150:151], v[56:57], v[154:155] op_sel_hi:[1,0]
	v_pk_mul_f32 v[152:153], v[58:59], v[154:155] op_sel_hi:[1,0]
	v_pk_mul_f32 v[150:151], v[132:133], v[150:151]
	v_pk_mul_f32 v[152:153], v[134:135], v[152:153]
	v_cvt_pk_bf16_f32 v150, v150, v151
	v_pk_mul_f32 v[154:155], v[26:27], v[154:155] op_sel_hi:[1,0]
	v_cvt_pk_bf16_f32 v151, v152, v153
	v_mul_f32_e32 v152, v119, v119
	v_fmac_f32_e32 v152, v118, v118
	v_add_f32_e32 v145, v145, v152
	v_mul_f32_e32 v152, v85, v85
	v_mul_f32_e32 v153, v87, v87
	v_fmac_f32_e32 v152, v84, v84
	v_fmac_f32_e32 v153, v86, v86
	v_add_f32_e32 v152, v152, v153
	v_add_f32_e32 v145, v145, v152
	v_mul_f32_e32 v152, v53, v53
	v_mul_f32_e32 v153, v55, v55
	v_fmac_f32_e32 v152, v52, v52
	v_fmac_f32_e32 v153, v54, v54
	v_add_f32_e32 v152, v152, v153
	v_add_f32_e32 v145, v145, v152
	v_mul_f32_e32 v152, v21, v21
	v_mul_f32_e32 v153, v23, v23
	v_fmac_f32_e32 v152, v20, v20
	v_fmac_f32_e32 v153, v22, v22
	v_add_f32_e32 v152, v152, v153
	v_add_f32_e32 v145, v145, v152
	v_mov_b32_e32 v152, v145
	s_nop 1
	v_permlane16_swap_b32_e32 v145, v152
	v_add_f32_e32 v145, v145, v152
	v_mov_b32_e32 v152, v145
	s_nop 1
	v_permlane32_swap_b32_e32 v145, v152
	v_add_f32_e32 v145, v145, v152
	v_fmamk_f32 v145, v145, 0x3c800000, v149
	v_rsq_f32_e32 v160, v145
	v_pk_mul_f32 v[154:155], v[130:131], v[154:155]
	v_pk_mul_f32 v[158:159], v[128:129], v[158:159]
	s_mov_b32 s4, 0x8000
	v_cvt_pk_bf16_f32 v152, v158, v159
	v_cvt_pk_bf16_f32 v153, v154, v155
	global_store_dwordx4 v[156:157], v[150:153], off offset:64
	v_pk_mul_f32 v[154:155], v[84:85], v[160:161] op_sel_hi:[1,0]
	v_pk_mul_f32 v[156:157], v[86:87], v[160:161] op_sel_hi:[1,0]
	v_pk_mul_f32 v[150:151], v[116:117], v[160:161] op_sel_hi:[1,0]
	v_pk_mul_f32 v[152:153], v[118:119], v[160:161] op_sel_hi:[1,0]
	v_pk_mul_f32 v[150:151], v[140:141], v[150:151]
	v_pk_mul_f32 v[152:153], v[142:143], v[152:153]
	v_pk_mul_f32 v[154:155], v[136:137], v[154:155]
	v_cvt_pk_bf16_f32 v150, v150, v151
	v_cvt_pk_bf16_f32 v151, v152, v153
	v_pk_mul_f32 v[156:157], v[138:139], v[156:157]
	v_cvt_pk_bf16_f32 v152, v154, v155
	v_add_co_u32_e32 v154, vcc, s4, v146
	v_cvt_pk_bf16_f32 v153, v156, v157
	v_mul_f32_e32 v145, v113, v113
	s_nop 0
	v_addc_co_u32_e32 v155, vcc, 0, v147, vcc
	global_store_dwordx4 v[154:155], v[150:153], off
	v_fmac_f32_e32 v145, v112, v112
	v_pk_mul_f32 v[156:157], v[20:21], v[160:161] op_sel_hi:[1,0]
	v_pk_mul_f32 v[150:151], v[52:53], v[160:161] op_sel_hi:[1,0]
	v_pk_mul_f32 v[152:153], v[54:55], v[160:161] op_sel_hi:[1,0]
	v_pk_mul_f32 v[150:151], v[132:133], v[150:151]
	v_pk_mul_f32 v[152:153], v[134:135], v[152:153]
	v_cvt_pk_bf16_f32 v150, v150, v151
	v_pk_mul_f32 v[158:159], v[22:23], v[160:161] op_sel_hi:[1,0]
	v_cvt_pk_bf16_f32 v151, v152, v153
	v_mul_f32_e32 v152, v115, v115
	v_fmac_f32_e32 v152, v114, v114
	v_add_f32_e32 v145, v145, v152
	v_mul_f32_e32 v152, v81, v81
	v_mul_f32_e32 v153, v83, v83
	v_fmac_f32_e32 v152, v80, v80
	v_fmac_f32_e32 v153, v82, v82
	v_add_f32_e32 v152, v152, v153
	v_add_f32_e32 v145, v145, v152
	v_mul_f32_e32 v152, v49, v49
	v_mul_f32_e32 v153, v51, v51
	v_fmac_f32_e32 v152, v48, v48
	v_fmac_f32_e32 v153, v50, v50
	v_add_f32_e32 v152, v152, v153
	v_add_f32_e32 v145, v145, v152
	v_mul_f32_e32 v152, v17, v17
	v_mul_f32_e32 v153, v19, v19
	v_fmac_f32_e32 v152, v16, v16
	v_fmac_f32_e32 v153, v18, v18
	v_add_f32_e32 v152, v152, v153
	v_add_f32_e32 v145, v145, v152
	v_mov_b32_e32 v152, v145
	s_nop 1
	v_permlane16_swap_b32_e32 v145, v152
	v_add_f32_e32 v145, v145, v152
	v_mov_b32_e32 v152, v145
	s_nop 1
	v_permlane32_swap_b32_e32 v145, v152
	v_add_f32_e32 v145, v145, v152
	v_fmamk_f32 v145, v145, 0x3c800000, v149
	v_rsq_f32_e32 v160, v145
	v_pk_mul_f32 v[158:159], v[130:131], v[158:159]
	v_pk_mul_f32 v[156:157], v[128:129], v[156:157]
	s_mov_b32 s4, 0xc000
	v_cvt_pk_bf16_f32 v152, v156, v157
	v_cvt_pk_bf16_f32 v153, v158, v159
	global_store_dwordx4 v[154:155], v[150:153], off offset:64
	v_pk_mul_f32 v[154:155], v[80:81], v[160:161] op_sel_hi:[1,0]
	v_pk_mul_f32 v[156:157], v[82:83], v[160:161] op_sel_hi:[1,0]
	v_pk_mul_f32 v[150:151], v[112:113], v[160:161] op_sel_hi:[1,0]
	v_pk_mul_f32 v[152:153], v[114:115], v[160:161] op_sel_hi:[1,0]
	v_pk_mul_f32 v[150:151], v[140:141], v[150:151]
	v_pk_mul_f32 v[152:153], v[142:143], v[152:153]
	v_pk_mul_f32 v[154:155], v[136:137], v[154:155]
	v_cvt_pk_bf16_f32 v150, v150, v151
	v_cvt_pk_bf16_f32 v151, v152, v153
	v_pk_mul_f32 v[156:157], v[138:139], v[156:157]
	v_cvt_pk_bf16_f32 v152, v154, v155
	v_add_co_u32_e32 v154, vcc, s4, v146
	v_cvt_pk_bf16_f32 v153, v156, v157
	v_mul_f32_e32 v145, v109, v109
	s_nop 0
	v_addc_co_u32_e32 v155, vcc, 0, v147, vcc
	global_store_dwordx4 v[154:155], v[150:153], off
	v_fmac_f32_e32 v145, v108, v108
	v_pk_mul_f32 v[156:157], v[16:17], v[160:161] op_sel_hi:[1,0]
	v_pk_mul_f32 v[150:151], v[48:49], v[160:161] op_sel_hi:[1,0]
	v_pk_mul_f32 v[152:153], v[50:51], v[160:161] op_sel_hi:[1,0]
	v_pk_mul_f32 v[150:151], v[132:133], v[150:151]
	v_pk_mul_f32 v[152:153], v[134:135], v[152:153]
	v_cvt_pk_bf16_f32 v150, v150, v151
	v_pk_mul_f32 v[158:159], v[18:19], v[160:161] op_sel_hi:[1,0]
	v_cvt_pk_bf16_f32 v151, v152, v153
	v_mul_f32_e32 v152, v111, v111
	v_fmac_f32_e32 v152, v110, v110
	v_add_f32_e32 v145, v145, v152
	v_mul_f32_e32 v152, v77, v77
	v_mul_f32_e32 v153, v79, v79
	v_fmac_f32_e32 v152, v76, v76
	v_fmac_f32_e32 v153, v78, v78
	v_add_f32_e32 v152, v152, v153
	v_add_f32_e32 v145, v145, v152
	v_mul_f32_e32 v152, v45, v45
	v_mul_f32_e32 v153, v47, v47
	v_fmac_f32_e32 v152, v44, v44
	v_fmac_f32_e32 v153, v46, v46
	v_add_f32_e32 v152, v152, v153
	v_add_f32_e32 v145, v145, v152
	v_mul_f32_e32 v152, v13, v13
	v_mul_f32_e32 v153, v15, v15
	v_fmac_f32_e32 v152, v12, v12
	v_fmac_f32_e32 v153, v14, v14
	v_add_f32_e32 v152, v152, v153
	v_add_f32_e32 v145, v145, v152
	v_mov_b32_e32 v152, v145
	s_nop 1
	v_permlane16_swap_b32_e32 v145, v152
	v_add_f32_e32 v145, v145, v152
	v_mov_b32_e32 v152, v145
	s_nop 1
	v_permlane32_swap_b32_e32 v145, v152
	v_add_f32_e32 v145, v145, v152
	v_fmamk_f32 v145, v145, 0x3c800000, v149
	v_rsq_f32_e32 v160, v145
	v_pk_mul_f32 v[158:159], v[130:131], v[158:159]
	v_pk_mul_f32 v[156:157], v[128:129], v[156:157]
	s_mov_b32 s4, 0x20000
	v_cvt_pk_bf16_f32 v152, v156, v157
	v_cvt_pk_bf16_f32 v153, v158, v159
	global_store_dwordx4 v[154:155], v[150:153], off offset:64
	v_pk_mul_f32 v[154:155], v[76:77], v[160:161] op_sel_hi:[1,0]
	v_pk_mul_f32 v[156:157], v[78:79], v[160:161] op_sel_hi:[1,0]
	v_pk_mul_f32 v[150:151], v[108:109], v[160:161] op_sel_hi:[1,0]
	v_pk_mul_f32 v[152:153], v[110:111], v[160:161] op_sel_hi:[1,0]
	v_pk_mul_f32 v[150:151], v[140:141], v[150:151]
	v_pk_mul_f32 v[152:153], v[142:143], v[152:153]
	v_pk_mul_f32 v[154:155], v[136:137], v[154:155]
	v_cvt_pk_bf16_f32 v150, v150, v151
	v_cvt_pk_bf16_f32 v151, v152, v153
	v_pk_mul_f32 v[156:157], v[138:139], v[156:157]
	v_cvt_pk_bf16_f32 v152, v154, v155
	v_add_co_u32_e32 v154, vcc, s4, v146
	v_cvt_pk_bf16_f32 v153, v156, v157
	v_mul_f32_e32 v145, v105, v105
	s_nop 0
	v_addc_co_u32_e32 v155, vcc, 0, v147, vcc
	global_store_dwordx4 v[154:155], v[150:153], off
	v_fmac_f32_e32 v145, v104, v104
	v_pk_mul_f32 v[156:157], v[12:13], v[160:161] op_sel_hi:[1,0]
	v_pk_mul_f32 v[150:151], v[44:45], v[160:161] op_sel_hi:[1,0]
	v_pk_mul_f32 v[152:153], v[46:47], v[160:161] op_sel_hi:[1,0]
	v_pk_mul_f32 v[150:151], v[132:133], v[150:151]
	v_pk_mul_f32 v[152:153], v[134:135], v[152:153]
	v_cvt_pk_bf16_f32 v150, v150, v151
	v_pk_mul_f32 v[158:159], v[14:15], v[160:161] op_sel_hi:[1,0]
	v_cvt_pk_bf16_f32 v151, v152, v153
	v_mul_f32_e32 v152, v107, v107
	v_fmac_f32_e32 v152, v106, v106
	v_add_f32_e32 v145, v145, v152
	v_mul_f32_e32 v152, v73, v73
	v_mul_f32_e32 v153, v75, v75
	v_fmac_f32_e32 v152, v72, v72
	v_fmac_f32_e32 v153, v74, v74
	v_add_f32_e32 v152, v152, v153
	v_add_f32_e32 v145, v145, v152
	v_mul_f32_e32 v152, v41, v41
	v_mul_f32_e32 v153, v43, v43
	v_fmac_f32_e32 v152, v40, v40
	v_fmac_f32_e32 v153, v42, v42
	v_add_f32_e32 v152, v152, v153
	v_add_f32_e32 v145, v145, v152
	v_mul_f32_e32 v152, v9, v9
	v_mul_f32_e32 v153, v11, v11
	v_fmac_f32_e32 v152, v8, v8
	v_fmac_f32_e32 v153, v10, v10
	v_add_f32_e32 v152, v152, v153
	v_add_f32_e32 v145, v145, v152
	v_mov_b32_e32 v152, v145
	s_nop 1
	v_permlane16_swap_b32_e32 v145, v152
	v_add_f32_e32 v145, v145, v152
	v_mov_b32_e32 v152, v145
	s_nop 1
	v_permlane32_swap_b32_e32 v145, v152
	v_add_f32_e32 v145, v145, v152
	v_fmamk_f32 v145, v145, 0x3c800000, v149
	v_rsq_f32_e32 v160, v145
	v_pk_mul_f32 v[158:159], v[130:131], v[158:159]
	v_pk_mul_f32 v[156:157], v[128:129], v[156:157]
	s_mov_b32 s4, 0x24000
	v_cvt_pk_bf16_f32 v152, v156, v157
	v_cvt_pk_bf16_f32 v153, v158, v159
	global_store_dwordx4 v[154:155], v[150:153], off offset:64
	v_pk_mul_f32 v[154:155], v[72:73], v[160:161] op_sel_hi:[1,0]
	v_pk_mul_f32 v[156:157], v[74:75], v[160:161] op_sel_hi:[1,0]
	v_pk_mul_f32 v[150:151], v[104:105], v[160:161] op_sel_hi:[1,0]
	v_pk_mul_f32 v[152:153], v[106:107], v[160:161] op_sel_hi:[1,0]
	v_pk_mul_f32 v[150:151], v[140:141], v[150:151]
	v_pk_mul_f32 v[152:153], v[142:143], v[152:153]
	v_pk_mul_f32 v[154:155], v[136:137], v[154:155]
	v_cvt_pk_bf16_f32 v150, v150, v151
	v_cvt_pk_bf16_f32 v151, v152, v153
	v_pk_mul_f32 v[156:157], v[138:139], v[156:157]
	v_cvt_pk_bf16_f32 v152, v154, v155
	v_add_co_u32_e32 v154, vcc, s4, v146
	v_cvt_pk_bf16_f32 v153, v156, v157
	v_mul_f32_e32 v145, v101, v101
	s_nop 0
	v_addc_co_u32_e32 v155, vcc, 0, v147, vcc
	global_store_dwordx4 v[154:155], v[150:153], off
	v_fmac_f32_e32 v145, v100, v100
	v_pk_mul_f32 v[156:157], v[8:9], v[160:161] op_sel_hi:[1,0]
	v_pk_mul_f32 v[150:151], v[40:41], v[160:161] op_sel_hi:[1,0]
	v_pk_mul_f32 v[152:153], v[42:43], v[160:161] op_sel_hi:[1,0]
	v_pk_mul_f32 v[150:151], v[132:133], v[150:151]
	v_pk_mul_f32 v[152:153], v[134:135], v[152:153]
	v_cvt_pk_bf16_f32 v150, v150, v151
	v_pk_mul_f32 v[158:159], v[10:11], v[160:161] op_sel_hi:[1,0]
	v_cvt_pk_bf16_f32 v151, v152, v153
	v_mul_f32_e32 v152, v103, v103
	v_fmac_f32_e32 v152, v102, v102
	v_add_f32_e32 v145, v145, v152
	v_mul_f32_e32 v152, v69, v69
	v_mul_f32_e32 v153, v71, v71
	v_fmac_f32_e32 v152, v68, v68
	v_fmac_f32_e32 v153, v70, v70
	v_add_f32_e32 v152, v152, v153
	v_add_f32_e32 v145, v145, v152
	v_mul_f32_e32 v152, v37, v37
	v_mul_f32_e32 v153, v39, v39
	v_fmac_f32_e32 v152, v36, v36
	v_fmac_f32_e32 v153, v38, v38
	v_add_f32_e32 v152, v152, v153
	v_add_f32_e32 v145, v145, v152
	v_mul_f32_e32 v152, v5, v5
	v_mul_f32_e32 v153, v7, v7
	v_fmac_f32_e32 v152, v4, v4
	v_fmac_f32_e32 v153, v6, v6
	v_add_f32_e32 v152, v152, v153
	v_add_f32_e32 v145, v145, v152
	v_mov_b32_e32 v152, v145
	s_nop 1
	v_permlane16_swap_b32_e32 v145, v152
	v_add_f32_e32 v145, v145, v152
	v_mov_b32_e32 v152, v145
	s_nop 1
	v_permlane32_swap_b32_e32 v145, v152
	v_add_f32_e32 v145, v145, v152
	v_fmamk_f32 v145, v145, 0x3c800000, v149
	v_rsq_f32_e32 v160, v145
	v_pk_mul_f32 v[158:159], v[130:131], v[158:159]
	v_pk_mul_f32 v[156:157], v[128:129], v[156:157]
	s_mov_b32 s4, 0x28000
	v_cvt_pk_bf16_f32 v152, v156, v157
	v_cvt_pk_bf16_f32 v153, v158, v159
	global_store_dwordx4 v[154:155], v[150:153], off offset:64
	v_pk_mul_f32 v[154:155], v[68:69], v[160:161] op_sel_hi:[1,0]
	v_pk_mul_f32 v[156:157], v[70:71], v[160:161] op_sel_hi:[1,0]
	v_pk_mul_f32 v[150:151], v[100:101], v[160:161] op_sel_hi:[1,0]
	v_pk_mul_f32 v[152:153], v[102:103], v[160:161] op_sel_hi:[1,0]
	v_pk_mul_f32 v[150:151], v[140:141], v[150:151]
	v_pk_mul_f32 v[152:153], v[142:143], v[152:153]
	v_pk_mul_f32 v[154:155], v[136:137], v[154:155]
	v_cvt_pk_bf16_f32 v150, v150, v151
	v_cvt_pk_bf16_f32 v151, v152, v153
	v_pk_mul_f32 v[156:157], v[138:139], v[156:157]
	v_cvt_pk_bf16_f32 v152, v154, v155
	v_add_co_u32_e32 v154, vcc, s4, v146
	v_cvt_pk_bf16_f32 v153, v156, v157
	v_mul_f32_e32 v145, v97, v97
	s_nop 0
	v_addc_co_u32_e32 v155, vcc, 0, v147, vcc
	global_store_dwordx4 v[154:155], v[150:153], off
	v_fmac_f32_e32 v145, v96, v96
	v_pk_mul_f32 v[156:157], v[4:5], v[160:161] op_sel_hi:[1,0]
	v_pk_mul_f32 v[150:151], v[36:37], v[160:161] op_sel_hi:[1,0]
	v_pk_mul_f32 v[152:153], v[38:39], v[160:161] op_sel_hi:[1,0]
	v_pk_mul_f32 v[150:151], v[132:133], v[150:151]
	v_pk_mul_f32 v[152:153], v[134:135], v[152:153]
	v_cvt_pk_bf16_f32 v150, v150, v151
	v_pk_mul_f32 v[158:159], v[6:7], v[160:161] op_sel_hi:[1,0]
	v_cvt_pk_bf16_f32 v151, v152, v153
	v_mul_f32_e32 v152, v99, v99
	v_fmac_f32_e32 v152, v98, v98
	v_add_f32_e32 v145, v145, v152
	v_mul_f32_e32 v152, v65, v65
	v_mul_f32_e32 v153, v67, v67
	v_fmac_f32_e32 v152, v64, v64
	v_fmac_f32_e32 v153, v66, v66
	v_add_f32_e32 v152, v152, v153
	v_add_f32_e32 v145, v145, v152
	v_mul_f32_e32 v152, v33, v33
	v_mul_f32_e32 v153, v35, v35
	v_fmac_f32_e32 v152, v32, v32
	v_fmac_f32_e32 v153, v34, v34
	v_add_f32_e32 v152, v152, v153
	v_add_f32_e32 v145, v145, v152
	v_mul_f32_e32 v152, v1, v1
	v_mul_f32_e32 v153, v3, v3
	v_fmac_f32_e32 v152, v0, v0
	v_fmac_f32_e32 v153, v2, v2
	v_add_f32_e32 v152, v152, v153
	v_add_f32_e32 v145, v145, v152
	v_mov_b32_e32 v152, v145
	s_nop 1
	v_permlane16_swap_b32_e32 v145, v152
	v_add_f32_e32 v145, v145, v152
	v_mov_b32_e32 v152, v145
	s_nop 1
	v_permlane32_swap_b32_e32 v145, v152
	v_add_f32_e32 v145, v145, v152
	v_fmac_f32_e32 v149, 0x3c800000, v145
	v_rsq_f32_e32 v160, v149
	v_pk_mul_f32 v[158:159], v[130:131], v[158:159]
	v_pk_mul_f32 v[156:157], v[128:129], v[156:157]
	s_mov_b32 s4, 0x2c000
	v_cvt_pk_bf16_f32 v152, v156, v157
	v_cvt_pk_bf16_f32 v153, v158, v159
	global_store_dwordx4 v[154:155], v[150:153], off offset:64
	s_nop 1
	v_pk_mul_f32 v[150:151], v[96:97], v[160:161] op_sel_hi:[1,0]
	v_pk_mul_f32 v[152:153], v[98:99], v[160:161] op_sel_hi:[1,0]
	v_pk_mul_f32 v[140:141], v[140:141], v[150:151]
	v_pk_mul_f32 v[142:143], v[142:143], v[152:153]
	v_pk_mul_f32 v[150:151], v[64:65], v[160:161] op_sel_hi:[1,0]
	v_pk_mul_f32 v[152:153], v[66:67], v[160:161] op_sel_hi:[1,0]
	s_nop 0
	v_pk_mul_f32 v[152:153], v[138:139], v[152:153]
	v_pk_mul_f32 v[138:139], v[136:137], v[150:151]
	v_cvt_pk_bf16_f32 v136, v140, v141
	v_add_co_u32_e32 v140, vcc, s4, v146
	v_cvt_pk_bf16_f32 v137, v142, v143
	v_cvt_pk_bf16_f32 v138, v138, v139
	v_cvt_pk_bf16_f32 v139, v152, v153
	s_nop 1
	v_addc_co_u32_e32 v141, vcc, 0, v147, vcc
	global_store_dwordx4 v[140:141], v[136:139], off
	s_nop 1
	v_pk_mul_f32 v[136:137], v[32:33], v[160:161] op_sel_hi:[1,0]
	v_pk_mul_f32 v[138:139], v[34:35], v[160:161] op_sel_hi:[1,0]
	v_pk_mul_f32 v[132:133], v[132:133], v[136:137]
	v_pk_mul_f32 v[134:135], v[134:135], v[138:139]
	v_pk_mul_f32 v[136:137], v[0:1], v[160:161] op_sel_hi:[1,0]
	v_pk_mul_f32 v[138:139], v[2:3], v[160:161] op_sel_hi:[1,0]
	s_nop 0
	v_pk_mul_f32 v[138:139], v[130:131], v[138:139]
	v_pk_mul_f32 v[130:131], v[128:129], v[136:137]
	v_cvt_pk_bf16_f32 v128, v132, v133
	v_cvt_pk_bf16_f32 v129, v134, v135
	s_nop 0
	v_cvt_pk_bf16_f32 v130, v130, v131
	v_cvt_pk_bf16_f32 v131, v138, v139
	global_store_dwordx4 v[140:141], v[128:131], off offset:64

.LBB0_282:
	ds_read_b128 v[144:147], v164
	ds_read_b128 v[148:151], v164 offset:1024
	ds_read_b128 v[152:155], v164 offset:2048
	ds_read_b128 v[156:159], v164 offset:3072
	s_add_u32 s33, s0, 0xfffc0080
	s_addc_u32 s82, s1, -1
	s_cmp_eq_u32 s97, 12
	s_cselect_b32 s85, s4, s82
	s_cselect_b32 s84, s5, s33
	s_cselect_b32 s83, s57, s81
	s_cselect_b32 s82, s59, s67
	v_lshl_add_u64 v[160:161], s[0:1], 0, v[140:141]
	s_add_i32 m0, s13, 0xc000
	ds_read_b128 v[172:175], v165
	ds_read_b128 v[176:179], v165 offset:1024
	ds_read_b128 v[180:183], v165 offset:2048
	ds_read_b128 v[184:187], v165 offset:3072
	ds_read_b128 v[188:191], v165 offset:4096
	ds_read_b128 v[192:195], v165 offset:5120
	ds_read_b128 v[196:199], v165 offset:6144
	ds_read_b128 v[200:203], v165 offset:7168
	global_load_lds_dwordx4 v[160:161], off
	v_lshl_add_u64 v[160:161], s[0:1], 0, v[142:143]
	s_add_i32 m0, s13, 0xe000
	s_nop 0
	global_load_lds_dwordx4 v[160:161], off
	s_waitcnt lgkmcnt(8)
	s_barrier
	s_waitcnt lgkmcnt(0)
	s_waitcnt lgkmcnt(0)
	v_mfma_f32_16x16x32_bf16 v[124:127], v[144:147], v[172:175], v[124:127]
	v_mfma_f32_16x16x32_bf16 v[92:95], v[152:155], v[172:175], v[92:95]
	v_mfma_f32_16x16x32_bf16 v[120:123], v[144:147], v[180:183], v[120:123]
	v_mfma_f32_16x16x32_bf16 v[88:91], v[152:155], v[180:183], v[88:91]
	v_mfma_f32_16x16x32_bf16 v[116:119], v[144:147], v[188:191], v[116:119]
	v_mfma_f32_16x16x32_bf16 v[84:87], v[152:155], v[188:191], v[84:87]
	v_mfma_f32_16x16x32_bf16 v[112:115], v[144:147], v[196:199], v[112:115]
	v_mfma_f32_16x16x32_bf16 v[80:83], v[152:155], v[196:199], v[80:83]
	v_mfma_f32_16x16x32_bf16 v[124:127], v[148:151], v[176:179], v[124:127]
	v_mfma_f32_16x16x32_bf16 v[92:95], v[156:159], v[176:179], v[92:95]
	v_mfma_f32_16x16x32_bf16 v[120:123], v[148:151], v[184:187], v[120:123]
	v_mfma_f32_16x16x32_bf16 v[88:91], v[156:159], v[184:187], v[88:91]
	v_mfma_f32_16x16x32_bf16 v[116:119], v[148:151], v[192:195], v[116:119]
	v_mfma_f32_16x16x32_bf16 v[84:87], v[156:159], v[192:195], v[84:87]
	v_mfma_f32_16x16x32_bf16 v[112:115], v[148:151], v[200:203], v[112:115]
	v_mfma_f32_16x16x32_bf16 v[80:83], v[156:159], v[200:203], v[80:83]
	s_barrier
	s_add_i32 s33, s89, s11
	v_lshl_add_u64 v[160:161], s[82:83], 0, v[130:131]
	s_mov_b32 m0, s33
	ds_read_b128 v[204:207], v166
	ds_read_b128 v[208:211], v166 offset:1024
	ds_read_b128 v[212:215], v166 offset:2048
	ds_read_b128 v[218:221], v166 offset:3072
	global_load_lds_dwordx4 v[160:161], off
	v_lshl_add_u64 v[222:223], s[82:83], 0, v[134:135]
	s_add_i32 m0, s33, 0x2000
	s_nop 0
	global_load_lds_dwordx4 v[222:223], off
	s_barrier
	s_waitcnt lgkmcnt(0)
	s_waitcnt lgkmcnt(0)
	v_mfma_f32_16x16x32_bf16 v[60:63], v[204:207], v[172:175], v[60:63]
	v_mfma_f32_16x16x32_bf16 v[28:31], v[212:215], v[172:175], v[28:31]
	v_mfma_f32_16x16x32_bf16 v[56:59], v[204:207], v[180:183], v[56:59]
	v_mfma_f32_16x16x32_bf16 v[24:27], v[212:215], v[180:183], v[24:27]
	v_mfma_f32_16x16x32_bf16 v[52:55], v[204:207], v[188:191], v[52:55]
	v_mfma_f32_16x16x32_bf16 v[20:23], v[212:215], v[188:191], v[20:23]
	v_mfma_f32_16x16x32_bf16 v[48:51], v[204:207], v[196:199], v[48:51]
	v_mfma_f32_16x16x32_bf16 v[16:19], v[212:215], v[196:199], v[16:19]
	v_mfma_f32_16x16x32_bf16 v[60:63], v[208:211], v[176:179], v[60:63]
	v_mfma_f32_16x16x32_bf16 v[28:31], v[218:221], v[176:179], v[28:31]
	v_mfma_f32_16x16x32_bf16 v[56:59], v[208:211], v[184:187], v[56:59]
	v_mfma_f32_16x16x32_bf16 v[24:27], v[218:221], v[184:187], v[24:27]
	v_mfma_f32_16x16x32_bf16 v[52:55], v[208:211], v[192:195], v[52:55]
	v_mfma_f32_16x16x32_bf16 v[20:23], v[218:221], v[192:195], v[20:23]
	v_mfma_f32_16x16x32_bf16 v[48:51], v[208:211], v[200:203], v[48:51]
	v_mfma_f32_16x16x32_bf16 v[16:19], v[218:221], v[200:203], v[16:19]
	s_mov_b32 m0, s13
	v_lshl_add_u64 v[224:225], s[84:85], 0, v[128:129]
	s_barrier
	ds_read_b128 v[172:175], v165 offset:16384
	ds_read_b128 v[176:179], v165 offset:17408
	ds_read_b128 v[180:183], v165 offset:18432
	ds_read_b128 v[184:187], v165 offset:19456
	ds_read_b128 v[188:191], v165 offset:20480
	ds_read_b128 v[192:195], v165 offset:21504
	ds_read_b128 v[196:199], v165 offset:22528
	ds_read_b128 v[200:203], v165 offset:23552
	global_load_lds_dwordx4 v[224:225], off
	v_lshl_add_u64 v[226:227], s[84:85], 0, v[132:133]
	s_mov_b32 m0, s15
	s_nop 0
	global_load_lds_dwordx4 v[226:227], off
	s_barrier
	s_waitcnt lgkmcnt(0)
	s_waitcnt lgkmcnt(0)
	v_mfma_f32_16x16x32_bf16 v[108:111], v[144:147], v[172:175], v[108:111]
	v_mfma_f32_16x16x32_bf16 v[76:79], v[152:155], v[172:175], v[76:79]
	v_mfma_f32_16x16x32_bf16 v[104:107], v[144:147], v[180:183], v[104:107]
	v_mfma_f32_16x16x32_bf16 v[72:75], v[152:155], v[180:183], v[72:75]
	v_mfma_f32_16x16x32_bf16 v[100:103], v[144:147], v[188:191], v[100:103]
	v_mfma_f32_16x16x32_bf16 v[68:71], v[152:155], v[188:191], v[68:71]
	v_mfma_f32_16x16x32_bf16 v[96:99], v[144:147], v[196:199], v[96:99]
	v_mfma_f32_16x16x32_bf16 v[64:67], v[152:155], v[196:199], v[64:67]
	v_mfma_f32_16x16x32_bf16 v[108:111], v[148:151], v[176:179], v[108:111]
	v_mfma_f32_16x16x32_bf16 v[76:79], v[156:159], v[176:179], v[76:79]
	v_mfma_f32_16x16x32_bf16 v[104:107], v[148:151], v[184:187], v[104:107]
	v_mfma_f32_16x16x32_bf16 v[72:75], v[156:159], v[184:187], v[72:75]
	v_mfma_f32_16x16x32_bf16 v[100:103], v[148:151], v[192:195], v[100:103]
	v_mfma_f32_16x16x32_bf16 v[68:71], v[156:159], v[192:195], v[68:71]
	v_mfma_f32_16x16x32_bf16 v[96:99], v[148:151], v[200:203], v[96:99]
	v_mfma_f32_16x16x32_bf16 v[64:67], v[156:159], v[200:203], v[64:67]
	s_barrier
	s_add_u32 vcc_lo, s82, 0x40000
	s_addc_u32 vcc_hi, s83, 0
	s_add_i32 s33, s91, s11
	v_lshl_add_u64 v[144:145], vcc, 0, v[130:131]
	s_mov_b32 m0, s33
	s_nop 0
	global_load_lds_dwordx4 v[144:145], off
	v_lshl_add_u64 v[144:145], vcc, 0, v[134:135]
	s_add_i32 m0, s33, 0x2000
	s_nop 0
	global_load_lds_dwordx4 v[144:145], off
	s_waitcnt vmcnt(6)
	s_barrier
	v_mfma_f32_16x16x32_bf16 v[44:47], v[204:207], v[172:175], v[44:47]
	v_mfma_f32_16x16x32_bf16 v[12:15], v[212:215], v[172:175], v[12:15]
	v_mfma_f32_16x16x32_bf16 v[40:43], v[204:207], v[180:183], v[40:43]
	v_mfma_f32_16x16x32_bf16 v[8:11], v[212:215], v[180:183], v[8:11]
	v_mfma_f32_16x16x32_bf16 v[36:39], v[204:207], v[188:191], v[36:39]
	v_mfma_f32_16x16x32_bf16 v[4:7], v[212:215], v[188:191], v[4:7]
	v_mfma_f32_16x16x32_bf16 v[32:35], v[204:207], v[196:199], v[32:35]
	v_mfma_f32_16x16x32_bf16 v[0:3], v[212:215], v[196:199], v[0:3]
	v_mfma_f32_16x16x32_bf16 v[44:47], v[208:211], v[176:179], v[44:47]
	v_mfma_f32_16x16x32_bf16 v[12:15], v[218:221], v[176:179], v[12:15]
	v_mfma_f32_16x16x32_bf16 v[40:43], v[208:211], v[184:187], v[40:43]
	v_mfma_f32_16x16x32_bf16 v[8:11], v[218:221], v[184:187], v[8:11]
	v_mfma_f32_16x16x32_bf16 v[36:39], v[208:211], v[192:195], v[36:39]
	v_mfma_f32_16x16x32_bf16 v[4:7], v[218:221], v[192:195], v[4:7]
	v_mfma_f32_16x16x32_bf16 v[32:35], v[208:211], v[200:203], v[32:35]
	v_mfma_f32_16x16x32_bf16 v[0:3], v[218:221], v[200:203], v[0:3]
	s_add_i32 s33, 0, 0x18000
	v_add_u32_e32 v136, s33, v162
	s_barrier
	ds_read_b128 v[144:147], v136
	ds_read_b128 v[148:151], v136 offset:1024
	ds_read_b128 v[152:155], v136 offset:2048
	ds_read_b128 v[156:159], v136 offset:3072
	s_add_u32 s84, s84, 0x40000
	s_addc_u32 s85, s85, 0
	s_mov_b32 m0, s19
	v_lshl_add_u64 v[204:205], s[84:85], 0, v[128:129]
	ds_read_b128 v[172:175], v165 offset:32768
	ds_read_b128 v[176:179], v165 offset:33792
	ds_read_b128 v[180:183], v165 offset:34816
	ds_read_b128 v[184:187], v165 offset:35840
	ds_read_b128 v[188:191], v165 offset:36864
	ds_read_b128 v[192:195], v165 offset:37888
	ds_read_b128 v[196:199], v165 offset:38912
	ds_read_b128 v[200:203], v165 offset:39936
	global_load_lds_dwordx4 v[204:205], off
	v_lshl_add_u64 v[204:205], s[84:85], 0, v[132:133]
	s_mov_b32 m0, s37
	s_nop 0
	global_load_lds_dwordx4 v[204:205], off
	s_waitcnt lgkmcnt(8)
	s_barrier
	s_waitcnt lgkmcnt(0)
	s_waitcnt lgkmcnt(0)
	v_mfma_f32_16x16x32_bf16 v[124:127], v[144:147], v[172:175], v[124:127]
	v_mfma_f32_16x16x32_bf16 v[92:95], v[152:155], v[172:175], v[92:95]
	v_mfma_f32_16x16x32_bf16 v[120:123], v[144:147], v[180:183], v[120:123]
	v_mfma_f32_16x16x32_bf16 v[88:91], v[152:155], v[180:183], v[88:91]
	v_mfma_f32_16x16x32_bf16 v[116:119], v[144:147], v[188:191], v[116:119]
	v_mfma_f32_16x16x32_bf16 v[84:87], v[152:155], v[188:191], v[84:87]
	v_mfma_f32_16x16x32_bf16 v[112:115], v[144:147], v[196:199], v[112:115]
	v_mfma_f32_16x16x32_bf16 v[80:83], v[152:155], v[196:199], v[80:83]
	v_mfma_f32_16x16x32_bf16 v[124:127], v[148:151], v[176:179], v[124:127]
	v_mfma_f32_16x16x32_bf16 v[92:95], v[156:159], v[176:179], v[92:95]
	v_mfma_f32_16x16x32_bf16 v[120:123], v[148:151], v[184:187], v[120:123]
	v_mfma_f32_16x16x32_bf16 v[88:91], v[156:159], v[184:187], v[88:91]
	v_mfma_f32_16x16x32_bf16 v[116:119], v[148:151], v[192:195], v[116:119]
	v_mfma_f32_16x16x32_bf16 v[84:87], v[156:159], v[192:195], v[84:87]
	v_mfma_f32_16x16x32_bf16 v[112:115], v[148:151], v[200:203], v[112:115]
	v_mfma_f32_16x16x32_bf16 v[80:83], v[156:159], v[200:203], v[80:83]
	s_barrier
	s_add_i32 s84, 0, 0x1c000
	s_add_i32 s33, s33, s11
	v_add_u32_e32 v136, s84, v162
	v_lshl_add_u64 v[160:161], v[160:161], 0, s[6:7]
	s_mov_b32 m0, s33
	ds_read_b128 v[204:207], v136
	ds_read_b128 v[208:211], v136 offset:1024
	ds_read_b128 v[212:215], v136 offset:2048
	ds_read_b128 v[218:221], v136 offset:3072
	global_load_lds_dwordx4 v[160:161], off
	v_lshl_add_u64 v[160:161], v[222:223], 0, s[6:7]
	s_add_i32 m0, s33, 0x2000
	s_nop 0
	global_load_lds_dwordx4 v[160:161], off
	s_barrier
	s_waitcnt lgkmcnt(0)
	s_waitcnt lgkmcnt(0)
	v_mfma_f32_16x16x32_bf16 v[60:63], v[204:207], v[172:175], v[60:63]
	v_mfma_f32_16x16x32_bf16 v[28:31], v[212:215], v[172:175], v[28:31]
	v_mfma_f32_16x16x32_bf16 v[56:59], v[204:207], v[180:183], v[56:59]
	v_mfma_f32_16x16x32_bf16 v[24:27], v[212:215], v[180:183], v[24:27]
	v_mfma_f32_16x16x32_bf16 v[52:55], v[204:207], v[188:191], v[52:55]
	v_mfma_f32_16x16x32_bf16 v[20:23], v[212:215], v[188:191], v[20:23]
	v_mfma_f32_16x16x32_bf16 v[48:51], v[204:207], v[196:199], v[48:51]
	v_mfma_f32_16x16x32_bf16 v[16:19], v[212:215], v[196:199], v[16:19]
	v_mfma_f32_16x16x32_bf16 v[60:63], v[208:211], v[176:179], v[60:63]
	v_mfma_f32_16x16x32_bf16 v[28:31], v[218:221], v[176:179], v[28:31]
	v_mfma_f32_16x16x32_bf16 v[56:59], v[208:211], v[184:187], v[56:59]
	v_mfma_f32_16x16x32_bf16 v[24:27], v[218:221], v[184:187], v[24:27]
	v_mfma_f32_16x16x32_bf16 v[52:55], v[208:211], v[192:195], v[52:55]
	v_mfma_f32_16x16x32_bf16 v[20:23], v[218:221], v[192:195], v[20:23]
	v_mfma_f32_16x16x32_bf16 v[48:51], v[208:211], v[200:203], v[48:51]
	v_mfma_f32_16x16x32_bf16 v[16:19], v[218:221], v[200:203], v[16:19]
	s_mov_b32 m0, s86
	v_lshl_add_u64 v[160:161], v[224:225], 0, s[6:7]
	s_barrier
	ds_read_b128 v[172:175], v165 offset:49152
	ds_read_b128 v[176:179], v165 offset:50176
	ds_read_b128 v[180:183], v165 offset:51200
	ds_read_b128 v[184:187], v165 offset:52224
	ds_read_b128 v[188:191], v165 offset:53248
	ds_read_b128 v[192:195], v165 offset:54272
	ds_read_b128 v[196:199], v165 offset:55296
	ds_read_b128 v[200:203], v165 offset:56320
	global_load_lds_dwordx4 v[160:161], off
	v_lshl_add_u64 v[160:161], v[226:227], 0, s[6:7]
	s_mov_b32 m0, s87
	s_nop 0
	global_load_lds_dwordx4 v[160:161], off
	s_barrier
	s_waitcnt lgkmcnt(0)
	s_waitcnt lgkmcnt(0)
	v_mfma_f32_16x16x32_bf16 v[108:111], v[144:147], v[172:175], v[108:111]
	v_mfma_f32_16x16x32_bf16 v[76:79], v[152:155], v[172:175], v[76:79]
	v_mfma_f32_16x16x32_bf16 v[104:107], v[144:147], v[180:183], v[104:107]
	v_mfma_f32_16x16x32_bf16 v[72:75], v[152:155], v[180:183], v[72:75]
	v_mfma_f32_16x16x32_bf16 v[100:103], v[144:147], v[188:191], v[100:103]
	v_mfma_f32_16x16x32_bf16 v[68:71], v[152:155], v[188:191], v[68:71]
	v_mfma_f32_16x16x32_bf16 v[96:99], v[144:147], v[196:199], v[96:99]
	v_mfma_f32_16x16x32_bf16 v[64:67], v[152:155], v[196:199], v[64:67]
	v_mfma_f32_16x16x32_bf16 v[108:111], v[148:151], v[176:179], v[108:111]
	v_mfma_f32_16x16x32_bf16 v[76:79], v[156:159], v[176:179], v[76:79]
	v_mfma_f32_16x16x32_bf16 v[104:107], v[148:151], v[184:187], v[104:107]
	v_mfma_f32_16x16x32_bf16 v[72:75], v[156:159], v[184:187], v[72:75]
	v_mfma_f32_16x16x32_bf16 v[100:103], v[148:151], v[192:195], v[100:103]
	v_mfma_f32_16x16x32_bf16 v[68:71], v[156:159], v[192:195], v[68:71]
	v_mfma_f32_16x16x32_bf16 v[96:99], v[148:151], v[200:203], v[96:99]
	v_mfma_f32_16x16x32_bf16 v[64:67], v[156:159], v[200:203], v[64:67]
	s_barrier
	s_add_u32 s82, s82, 0x40080
	s_addc_u32 s83, s83, 0
	s_add_i32 s33, s84, s11
	v_lshl_add_u64 v[144:145], s[82:83], 0, v[130:131]
	s_mov_b32 m0, s33
	s_nop 0
	global_load_lds_dwordx4 v[144:145], off
	v_lshl_add_u64 v[144:145], s[82:83], 0, v[134:135]
	s_add_i32 m0, s33, 0x2000
	s_nop 0
	global_load_lds_dwordx4 v[144:145], off
	s_waitcnt vmcnt(6)
	s_barrier
	v_mfma_f32_16x16x32_bf16 v[44:47], v[204:207], v[172:175], v[44:47]
	v_mfma_f32_16x16x32_bf16 v[12:15], v[212:215], v[172:175], v[12:15]
	v_mfma_f32_16x16x32_bf16 v[40:43], v[204:207], v[180:183], v[40:43]
	v_mfma_f32_16x16x32_bf16 v[8:11], v[212:215], v[180:183], v[8:11]
	v_mfma_f32_16x16x32_bf16 v[36:39], v[204:207], v[188:191], v[36:39]
	v_mfma_f32_16x16x32_bf16 v[4:7], v[212:215], v[188:191], v[4:7]
	v_mfma_f32_16x16x32_bf16 v[32:35], v[204:207], v[196:199], v[32:35]
	v_mfma_f32_16x16x32_bf16 v[0:3], v[212:215], v[196:199], v[0:3]
	v_mfma_f32_16x16x32_bf16 v[44:47], v[208:211], v[176:179], v[44:47]
	v_mfma_f32_16x16x32_bf16 v[12:15], v[218:221], v[176:179], v[12:15]
	v_mfma_f32_16x16x32_bf16 v[40:43], v[208:211], v[184:187], v[40:43]
	v_mfma_f32_16x16x32_bf16 v[8:11], v[218:221], v[184:187], v[8:11]
	v_mfma_f32_16x16x32_bf16 v[36:39], v[208:211], v[192:195], v[36:39]
	v_mfma_f32_16x16x32_bf16 v[4:7], v[218:221], v[192:195], v[4:7]
	v_mfma_f32_16x16x32_bf16 v[32:35], v[208:211], v[200:203], v[32:35]
	v_mfma_f32_16x16x32_bf16 v[0:3], v[218:221], v[200:203], v[0:3]
	s_add_i32 s97, s97, 2
	s_add_u32 s0, s0, 0x100
	s_addc_u32 s1, s1, 0
	s_add_u32 s67, s67, 0x100
	s_addc_u32 s81, s81, 0
	s_cmp_gt_u32 s97, 13
	s_barrier
	s_cbranch_scc0 .LBB0_282
	s_ashr_i32 s59, s80, 1
	s_and_b32 s57, s80, 1
	s_cmp_lg_u32 s59, 5
	s_mov_b64 s[0:1], -1
	s_cbranch_scc0 .LBB0_362
	s_ashr_i32 s67, s66, 31
	s_lshl_b64 s[0:1], s[66:67], 8
	v_lshl_add_u64 v[144:145], s[0:1], 0, v[138:139]
	s_add_i32 s0, s59, -3
	s_cmp_gt_u32 s0, 1
	s_mov_b64 s[0:1], -1
	s_cbranch_scc0 .LBB0_359
	s_cmp_lt_u32 s80, 2
	s_mov_b64 s[0:1], s[48:49]
	s_cbranch_scc1 .LBB0_294
	s_cmp_lt_i32 s59, 2
	s_cbranch_scc1 .LBB0_290
	s_cmp_eq_u32 s59, 2
	s_mov_b64 s[80:81], -1
	s_cbranch_scc0 .LBB0_289
	v_readlane_b32 s68, v252, 0
	v_readlane_b32 s69, v252, 1
	s_mov_b64 s[80:81], 0
	v_readlane_b32 s70, v252, 2
	v_readlane_b32 s71, v252, 3
	v_readlane_b32 s72, v252, 4
	v_readlane_b32 s73, v252, 5
	v_readlane_b32 s74, v252, 6
	v_readlane_b32 s75, v252, 7
	s_mov_b64 s[0:1], s[68:69]

.LBB0_614:
	ds_read_b128 v[128:131], v164
	ds_read_b128 v[132:135], v164 offset:1024
	ds_read_b128 v[136:139], v164 offset:2048
	ds_read_b128 v[140:143], v164 offset:3072
	s_add_u32 s26, s24, 0xfffc0080
	s_addc_u32 s27, s25, -1
	s_cmp_eq_u32 s60, 12
	s_cselect_b32 s29, s17, s27
	s_cselect_b32 s28, s23, s26
	s_cselect_b32 s27, s15, s59
	s_cselect_b32 s26, s57, s58
	v_lshl_add_u64 v[196:197], s[24:25], 0, v[150:151]
	s_add_i32 m0, s36, 0xc000
	ds_read_b128 v[158:161], v165
	ds_read_b128 v[168:171], v165 offset:1024
	ds_read_b128 v[172:175], v165 offset:2048
	ds_read_b128 v[176:179], v165 offset:3072
	ds_read_b128 v[180:183], v165 offset:4096
	ds_read_b128 v[184:187], v165 offset:5120
	ds_read_b128 v[188:191], v165 offset:6144
	ds_read_b128 v[192:195], v165 offset:7168
	global_load_lds_dwordx4 v[196:197], off
	v_lshl_add_u64 v[196:197], s[24:25], 0, v[152:153]
	s_add_i32 m0, s36, 0xe000
	s_nop 0
	global_load_lds_dwordx4 v[196:197], off
	s_waitcnt lgkmcnt(8)
	s_barrier
	s_waitcnt lgkmcnt(0)
	s_waitcnt lgkmcnt(0)
	v_mfma_f32_16x16x32_bf16 v[124:127], v[128:131], v[158:161], v[124:127]
	v_mfma_f32_16x16x32_bf16 v[120:123], v[136:139], v[158:161], v[120:123]
	v_mfma_f32_16x16x32_bf16 v[116:119], v[128:131], v[172:175], v[116:119]
	v_mfma_f32_16x16x32_bf16 v[112:115], v[136:139], v[172:175], v[112:115]
	v_mfma_f32_16x16x32_bf16 v[104:107], v[128:131], v[180:183], v[104:107]
	v_mfma_f32_16x16x32_bf16 v[96:99], v[136:139], v[180:183], v[96:99]
	v_mfma_f32_16x16x32_bf16 v[92:95], v[128:131], v[188:191], v[92:95]
	v_mfma_f32_16x16x32_bf16 v[76:79], v[136:139], v[188:191], v[76:79]
	v_mfma_f32_16x16x32_bf16 v[124:127], v[132:135], v[168:171], v[124:127]
	v_mfma_f32_16x16x32_bf16 v[120:123], v[140:143], v[168:171], v[120:123]
	v_mfma_f32_16x16x32_bf16 v[116:119], v[132:135], v[176:179], v[116:119]
	v_mfma_f32_16x16x32_bf16 v[112:115], v[140:143], v[176:179], v[112:115]
	v_mfma_f32_16x16x32_bf16 v[104:107], v[132:135], v[184:187], v[104:107]
	v_mfma_f32_16x16x32_bf16 v[96:99], v[140:143], v[184:187], v[96:99]
	v_mfma_f32_16x16x32_bf16 v[92:95], v[132:135], v[192:195], v[92:95]
	v_mfma_f32_16x16x32_bf16 v[76:79], v[140:143], v[192:195], v[76:79]
	s_barrier
	s_add_i32 s61, s48, s35
	v_lshl_add_u64 v[212:213], s[26:27], 0, v[144:145]
	s_mov_b32 m0, s61
	ds_read_b128 v[196:199], v166
	ds_read_b128 v[200:203], v166 offset:1024
	ds_read_b128 v[204:207], v166 offset:2048
	ds_read_b128 v[208:211], v166 offset:3072
	global_load_lds_dwordx4 v[212:213], off
	v_lshl_add_u64 v[214:215], s[26:27], 0, v[146:147]
	s_add_i32 m0, s61, 0x2000
	s_nop 0
	global_load_lds_dwordx4 v[214:215], off
	s_barrier
	s_waitcnt lgkmcnt(0)
	s_waitcnt lgkmcnt(0)
	v_mfma_f32_16x16x32_bf16 v[108:111], v[196:199], v[158:161], v[108:111]
	v_mfma_f32_16x16x32_bf16 v[100:103], v[204:207], v[158:161], v[100:103]
	v_mfma_f32_16x16x32_bf16 v[88:91], v[196:199], v[172:175], v[88:91]
	v_mfma_f32_16x16x32_bf16 v[84:87], v[204:207], v[172:175], v[84:87]
	v_mfma_f32_16x16x32_bf16 v[80:83], v[196:199], v[180:183], v[80:83]
	v_mfma_f32_16x16x32_bf16 v[72:75], v[204:207], v[180:183], v[72:75]
	v_mfma_f32_16x16x32_bf16 v[68:71], v[196:199], v[188:191], v[68:71]
	v_mfma_f32_16x16x32_bf16 v[64:67], v[204:207], v[188:191], v[64:67]
	v_mfma_f32_16x16x32_bf16 v[108:111], v[200:203], v[168:171], v[108:111]
	v_mfma_f32_16x16x32_bf16 v[100:103], v[208:211], v[168:171], v[100:103]
	v_mfma_f32_16x16x32_bf16 v[88:91], v[200:203], v[176:179], v[88:91]
	v_mfma_f32_16x16x32_bf16 v[84:87], v[208:211], v[176:179], v[84:87]
	v_mfma_f32_16x16x32_bf16 v[80:83], v[200:203], v[184:187], v[80:83]
	v_mfma_f32_16x16x32_bf16 v[72:75], v[208:211], v[184:187], v[72:75]
	v_mfma_f32_16x16x32_bf16 v[68:71], v[200:203], v[192:195], v[68:71]
	v_mfma_f32_16x16x32_bf16 v[64:67], v[208:211], v[192:195], v[64:67]
	s_mov_b32 m0, s36
	v_lshl_add_u64 v[216:217], s[28:29], 0, v[144:145]
	s_barrier
	ds_read_b128 v[158:161], v165 offset:16384
	ds_read_b128 v[168:171], v165 offset:17408
	ds_read_b128 v[172:175], v165 offset:18432
	ds_read_b128 v[176:179], v165 offset:19456
	ds_read_b128 v[180:183], v165 offset:20480
	ds_read_b128 v[184:187], v165 offset:21504
	ds_read_b128 v[188:191], v165 offset:22528
	ds_read_b128 v[192:195], v165 offset:23552
	global_load_lds_dwordx4 v[216:217], off
	v_lshl_add_u64 v[218:219], s[28:29], 0, v[146:147]
	s_mov_b32 m0, s37
	s_nop 0
	global_load_lds_dwordx4 v[218:219], off
	s_barrier
	s_waitcnt lgkmcnt(0)
	s_waitcnt lgkmcnt(0)
	v_mfma_f32_16x16x32_bf16 v[60:63], v[128:131], v[158:161], v[60:63]
	v_mfma_f32_16x16x32_bf16 v[56:59], v[136:139], v[158:161], v[56:59]
	v_mfma_f32_16x16x32_bf16 v[52:55], v[128:131], v[172:175], v[52:55]
	v_mfma_f32_16x16x32_bf16 v[48:51], v[136:139], v[172:175], v[48:51]
	v_mfma_f32_16x16x32_bf16 v[44:47], v[128:131], v[180:183], v[44:47]
	v_mfma_f32_16x16x32_bf16 v[24:27], v[136:139], v[180:183], v[24:27]
	v_mfma_f32_16x16x32_bf16 v[20:23], v[128:131], v[188:191], v[20:23]
	v_mfma_f32_16x16x32_bf16 v[8:11], v[136:139], v[188:191], v[8:11]
	v_mfma_f32_16x16x32_bf16 v[60:63], v[132:135], v[168:171], v[60:63]
	v_mfma_f32_16x16x32_bf16 v[56:59], v[140:143], v[168:171], v[56:59]
	v_mfma_f32_16x16x32_bf16 v[52:55], v[132:135], v[176:179], v[52:55]
	v_mfma_f32_16x16x32_bf16 v[48:51], v[140:143], v[176:179], v[48:51]
	v_mfma_f32_16x16x32_bf16 v[44:47], v[132:135], v[184:187], v[44:47]
	v_mfma_f32_16x16x32_bf16 v[24:27], v[140:143], v[184:187], v[24:27]
	v_mfma_f32_16x16x32_bf16 v[20:23], v[132:135], v[192:195], v[20:23]
	v_mfma_f32_16x16x32_bf16 v[8:11], v[140:143], v[192:195], v[8:11]
	s_barrier
	s_add_u32 s62, s26, 0x40000
	s_addc_u32 s63, s27, 0
	s_add_i32 s61, s49, s35
	v_lshl_add_u64 v[128:129], s[62:63], 0, v[144:145]
	s_mov_b32 m0, s61
	s_nop 0
	global_load_lds_dwordx4 v[128:129], off
	v_lshl_add_u64 v[128:129], s[62:63], 0, v[146:147]
	s_add_i32 m0, s61, 0x2000
	s_nop 0
	global_load_lds_dwordx4 v[128:129], off
	s_waitcnt vmcnt(6)
	s_barrier
	v_mfma_f32_16x16x32_bf16 v[40:43], v[196:199], v[158:161], v[40:43]
	v_mfma_f32_16x16x32_bf16 v[36:39], v[204:207], v[158:161], v[36:39]
	v_mfma_f32_16x16x32_bf16 v[32:35], v[196:199], v[172:175], v[32:35]
	v_mfma_f32_16x16x32_bf16 v[28:31], v[204:207], v[172:175], v[28:31]
	v_mfma_f32_16x16x32_bf16 v[16:19], v[196:199], v[180:183], v[16:19]
	v_mfma_f32_16x16x32_bf16 v[12:15], v[204:207], v[180:183], v[12:15]
	v_mfma_f32_16x16x32_bf16 v[4:7], v[196:199], v[188:191], v[4:7]
	v_mfma_f32_16x16x32_bf16 v[0:3], v[204:207], v[188:191], v[0:3]
	v_mfma_f32_16x16x32_bf16 v[40:43], v[200:203], v[168:171], v[40:43]
	v_mfma_f32_16x16x32_bf16 v[36:39], v[208:211], v[168:171], v[36:39]
	v_mfma_f32_16x16x32_bf16 v[32:35], v[200:203], v[176:179], v[32:35]
	v_mfma_f32_16x16x32_bf16 v[28:31], v[208:211], v[176:179], v[28:31]
	v_mfma_f32_16x16x32_bf16 v[16:19], v[200:203], v[184:187], v[16:19]
	v_mfma_f32_16x16x32_bf16 v[12:15], v[208:211], v[184:187], v[12:15]
	v_mfma_f32_16x16x32_bf16 v[4:7], v[200:203], v[192:195], v[4:7]
	v_mfma_f32_16x16x32_bf16 v[0:3], v[208:211], v[192:195], v[0:3]
	s_add_i32 s61, 0, 0x18000
	v_add_u32_e32 v140, s61, v162
	s_barrier
	ds_read_b128 v[128:131], v140
	ds_read_b128 v[132:135], v140 offset:1024
	ds_read_b128 v[136:139], v140 offset:2048
	ds_read_b128 v[140:143], v140 offset:3072
	s_add_u32 s28, s28, 0x40000
	s_addc_u32 s29, s29, 0
	s_mov_b32 m0, s40
	v_lshl_add_u64 v[196:197], s[28:29], 0, v[144:145]
	ds_read_b128 v[158:161], v165 offset:32768
	ds_read_b128 v[168:171], v165 offset:33792
	ds_read_b128 v[172:175], v165 offset:34816
	ds_read_b128 v[176:179], v165 offset:35840
	ds_read_b128 v[180:183], v165 offset:36864
	ds_read_b128 v[184:187], v165 offset:37888
	ds_read_b128 v[188:191], v165 offset:38912
	ds_read_b128 v[192:195], v165 offset:39936
	global_load_lds_dwordx4 v[196:197], off
	v_lshl_add_u64 v[196:197], s[28:29], 0, v[146:147]
	s_mov_b32 m0, s41
	s_nop 0
	global_load_lds_dwordx4 v[196:197], off
	s_waitcnt lgkmcnt(8)
	s_barrier
	s_waitcnt lgkmcnt(0)
	s_waitcnt lgkmcnt(0)
	v_mfma_f32_16x16x32_bf16 v[124:127], v[128:131], v[158:161], v[124:127]
	v_mfma_f32_16x16x32_bf16 v[120:123], v[136:139], v[158:161], v[120:123]
	v_mfma_f32_16x16x32_bf16 v[116:119], v[128:131], v[172:175], v[116:119]
	v_mfma_f32_16x16x32_bf16 v[112:115], v[136:139], v[172:175], v[112:115]
	v_mfma_f32_16x16x32_bf16 v[104:107], v[128:131], v[180:183], v[104:107]
	v_mfma_f32_16x16x32_bf16 v[96:99], v[136:139], v[180:183], v[96:99]
	v_mfma_f32_16x16x32_bf16 v[92:95], v[128:131], v[188:191], v[92:95]
	v_mfma_f32_16x16x32_bf16 v[76:79], v[136:139], v[188:191], v[76:79]
	v_mfma_f32_16x16x32_bf16 v[124:127], v[132:135], v[168:171], v[124:127]
	v_mfma_f32_16x16x32_bf16 v[120:123], v[140:143], v[168:171], v[120:123]
	v_mfma_f32_16x16x32_bf16 v[116:119], v[132:135], v[176:179], v[116:119]
	v_mfma_f32_16x16x32_bf16 v[112:115], v[140:143], v[176:179], v[112:115]
	v_mfma_f32_16x16x32_bf16 v[104:107], v[132:135], v[184:187], v[104:107]
	v_mfma_f32_16x16x32_bf16 v[96:99], v[140:143], v[184:187], v[96:99]
	v_mfma_f32_16x16x32_bf16 v[92:95], v[132:135], v[192:195], v[92:95]
	v_mfma_f32_16x16x32_bf16 v[76:79], v[140:143], v[192:195], v[76:79]
	s_barrier
	s_add_i32 s28, 0, 0x1c000
	s_add_i32 s29, s61, s35
	v_add_u32_e32 v167, s28, v162
	v_lshl_add_u64 v[212:213], v[212:213], 0, s[4:5]
	s_mov_b32 m0, s29
	ds_read_b128 v[196:199], v167
	ds_read_b128 v[200:203], v167 offset:1024
	ds_read_b128 v[204:207], v167 offset:2048
	ds_read_b128 v[208:211], v167 offset:3072
	global_load_lds_dwordx4 v[212:213], off
	v_lshl_add_u64 v[212:213], v[214:215], 0, s[4:5]
	s_add_i32 m0, s29, 0x2000
	s_nop 0
	global_load_lds_dwordx4 v[212:213], off
	s_barrier
	s_waitcnt lgkmcnt(0)
	s_waitcnt lgkmcnt(0)
	v_mfma_f32_16x16x32_bf16 v[108:111], v[196:199], v[158:161], v[108:111]
	v_mfma_f32_16x16x32_bf16 v[100:103], v[204:207], v[158:161], v[100:103]
	v_mfma_f32_16x16x32_bf16 v[88:91], v[196:199], v[172:175], v[88:91]
	v_mfma_f32_16x16x32_bf16 v[84:87], v[204:207], v[172:175], v[84:87]
	v_mfma_f32_16x16x32_bf16 v[80:83], v[196:199], v[180:183], v[80:83]
	v_mfma_f32_16x16x32_bf16 v[72:75], v[204:207], v[180:183], v[72:75]
	v_mfma_f32_16x16x32_bf16 v[68:71], v[196:199], v[188:191], v[68:71]
	v_mfma_f32_16x16x32_bf16 v[64:67], v[204:207], v[188:191], v[64:67]
	v_mfma_f32_16x16x32_bf16 v[108:111], v[200:203], v[168:171], v[108:111]
	v_mfma_f32_16x16x32_bf16 v[100:103], v[208:211], v[168:171], v[100:103]
	v_mfma_f32_16x16x32_bf16 v[88:91], v[200:203], v[176:179], v[88:91]
	v_mfma_f32_16x16x32_bf16 v[84:87], v[208:211], v[176:179], v[84:87]
	v_mfma_f32_16x16x32_bf16 v[80:83], v[200:203], v[184:187], v[80:83]
	v_mfma_f32_16x16x32_bf16 v[72:75], v[208:211], v[184:187], v[72:75]
	v_mfma_f32_16x16x32_bf16 v[68:71], v[200:203], v[192:195], v[68:71]
	v_mfma_f32_16x16x32_bf16 v[64:67], v[208:211], v[192:195], v[64:67]
	s_mov_b32 m0, s43
	v_lshl_add_u64 v[212:213], v[216:217], 0, s[4:5]
	s_barrier
	ds_read_b128 v[158:161], v165 offset:49152
	ds_read_b128 v[168:171], v165 offset:50176
	ds_read_b128 v[172:175], v165 offset:51200
	ds_read_b128 v[176:179], v165 offset:52224
	ds_read_b128 v[180:183], v165 offset:53248
	ds_read_b128 v[184:187], v165 offset:54272
	ds_read_b128 v[188:191], v165 offset:55296
	ds_read_b128 v[192:195], v165 offset:56320
	global_load_lds_dwordx4 v[212:213], off
	v_lshl_add_u64 v[212:213], v[218:219], 0, s[4:5]
	s_mov_b32 m0, s46
	s_nop 0
	global_load_lds_dwordx4 v[212:213], off
	s_barrier
	s_waitcnt lgkmcnt(0)
	s_waitcnt lgkmcnt(0)
	v_mfma_f32_16x16x32_bf16 v[60:63], v[128:131], v[158:161], v[60:63]
	v_mfma_f32_16x16x32_bf16 v[56:59], v[136:139], v[158:161], v[56:59]
	v_mfma_f32_16x16x32_bf16 v[52:55], v[128:131], v[172:175], v[52:55]
	v_mfma_f32_16x16x32_bf16 v[48:51], v[136:139], v[172:175], v[48:51]
	v_mfma_f32_16x16x32_bf16 v[44:47], v[128:131], v[180:183], v[44:47]
	v_mfma_f32_16x16x32_bf16 v[24:27], v[136:139], v[180:183], v[24:27]
	v_mfma_f32_16x16x32_bf16 v[20:23], v[128:131], v[188:191], v[20:23]
	v_mfma_f32_16x16x32_bf16 v[8:11], v[136:139], v[188:191], v[8:11]
	v_mfma_f32_16x16x32_bf16 v[60:63], v[132:135], v[168:171], v[60:63]
	v_mfma_f32_16x16x32_bf16 v[56:59], v[140:143], v[168:171], v[56:59]
	v_mfma_f32_16x16x32_bf16 v[52:55], v[132:135], v[176:179], v[52:55]
	v_mfma_f32_16x16x32_bf16 v[48:51], v[140:143], v[176:179], v[48:51]
	v_mfma_f32_16x16x32_bf16 v[44:47], v[132:135], v[184:187], v[44:47]
	v_mfma_f32_16x16x32_bf16 v[24:27], v[140:143], v[184:187], v[24:27]
	v_mfma_f32_16x16x32_bf16 v[20:23], v[132:135], v[192:195], v[20:23]
	v_mfma_f32_16x16x32_bf16 v[8:11], v[140:143], v[192:195], v[8:11]
	s_barrier
	s_add_u32 s26, s26, 0x40080
	s_addc_u32 s27, s27, 0
	s_add_i32 s28, s28, s35
	v_lshl_add_u64 v[128:129], s[26:27], 0, v[144:145]
	s_mov_b32 m0, s28
	s_nop 0
	global_load_lds_dwordx4 v[128:129], off
	v_lshl_add_u64 v[128:129], s[26:27], 0, v[146:147]
	s_add_i32 m0, s28, 0x2000
	s_nop 0
	global_load_lds_dwordx4 v[128:129], off
	s_waitcnt vmcnt(6)
	s_barrier
	v_mfma_f32_16x16x32_bf16 v[40:43], v[196:199], v[158:161], v[40:43]
	v_mfma_f32_16x16x32_bf16 v[36:39], v[204:207], v[158:161], v[36:39]
	v_mfma_f32_16x16x32_bf16 v[32:35], v[196:199], v[172:175], v[32:35]
	v_mfma_f32_16x16x32_bf16 v[28:31], v[204:207], v[172:175], v[28:31]
	v_mfma_f32_16x16x32_bf16 v[16:19], v[196:199], v[180:183], v[16:19]
	v_mfma_f32_16x16x32_bf16 v[12:15], v[204:207], v[180:183], v[12:15]
	v_mfma_f32_16x16x32_bf16 v[4:7], v[196:199], v[188:191], v[4:7]
	v_mfma_f32_16x16x32_bf16 v[0:3], v[204:207], v[188:191], v[0:3]
	v_mfma_f32_16x16x32_bf16 v[40:43], v[200:203], v[168:171], v[40:43]
	v_mfma_f32_16x16x32_bf16 v[36:39], v[208:211], v[168:171], v[36:39]
	v_mfma_f32_16x16x32_bf16 v[32:35], v[200:203], v[176:179], v[32:35]
	v_mfma_f32_16x16x32_bf16 v[28:31], v[208:211], v[176:179], v[28:31]
	v_mfma_f32_16x16x32_bf16 v[16:19], v[200:203], v[184:187], v[16:19]
	v_mfma_f32_16x16x32_bf16 v[12:15], v[208:211], v[184:187], v[12:15]
	v_mfma_f32_16x16x32_bf16 v[4:7], v[200:203], v[192:195], v[4:7]
	v_mfma_f32_16x16x32_bf16 v[0:3], v[208:211], v[192:195], v[0:3]
	s_add_i32 s60, s60, 2
	s_add_u32 s24, s24, 0x100
	s_addc_u32 s25, s25, 0
	s_add_u32 s58, s58, 0x100
	s_addc_u32 s59, s59, 0
	s_cmp_gt_u32 s60, 13
	s_barrier
	s_cbranch_scc0 .LBB0_614
	s_lshl_b32 s15, s22, 6
	s_and_b32 s24, s15, 0xfffffc00
	s_ashr_i32 s25, s24, 31
	s_ashr_i32 s23, s22, 31
	v_lshl_or_b32 v128, s56, 8, v163
	s_lshl_b64 s[24:25], s[24:25], 2
	s_add_u32 s24, s38, s24
	v_ashrrev_i32_e32 v129, 31, v128
	s_addc_u32 s25, s39, s25
	v_lshlrev_b64 v[232:233], 2, v[128:129]
	s_lshl_b64 s[22:23], s[22:23], 20
	v_lshl_add_u64 v[158:159], s[52:53], 0, v[232:233]
	v_lshl_add_u64 v[234:235], s[22:23], 0, v[148:149]
	v_lshl_add_u64 v[128:129], s[24:25], 0, v[232:233]
	v_lshl_add_u64 v[160:161], v[158:159], 0, v[234:235]
	v_or_b32_e32 v236, 0x10000, v234
	v_mov_b32_e32 v237, v235
	v_or_b32_e32 v238, 0x20000, v234
	v_mov_b32_e32 v239, v235
	v_or_b32_e32 v240, 0x30000, v234
	v_mov_b32_e32 v241, v235
	global_load_dwordx4 v[168:171], v[160:161], off nt
	global_load_dwordx4 v[140:143], v[128:129], off
	global_load_dwordx4 v[136:139], v[128:129], off offset:64
	global_load_dwordx4 v[172:175], v[160:161], off offset:64 nt
	global_load_dwordx4 v[176:179], v[160:161], off offset:512 nt
	global_load_dwordx4 v[132:135], v[128:129], off offset:512
	s_nop 0
	global_load_dwordx4 v[128:131], v[128:129], off offset:576
	s_nop 0
	global_load_dwordx4 v[180:183], v[160:161], off offset:576 nt
	v_lshl_add_u64 v[196:197], v[158:159], 0, v[236:237]
	v_lshl_add_u64 v[212:213], v[158:159], 0, v[238:239]
	v_lshl_add_u64 v[158:159], v[158:159], 0, v[240:241]
	global_load_dwordx4 v[184:187], v[196:197], off nt
	global_load_dwordx4 v[188:191], v[196:197], off offset:64 nt
	global_load_dwordx4 v[192:195], v[196:197], off offset:512 nt
	s_nop 0
	global_load_dwordx4 v[196:199], v[196:197], off offset:576 nt
	s_nop 0
	global_load_dwordx4 v[200:203], v[212:213], off nt
	global_load_dwordx4 v[204:207], v[212:213], off offset:64 nt
	global_load_dwordx4 v[208:211], v[212:213], off offset:512 nt
	s_nop 0
	global_load_dwordx4 v[212:215], v[212:213], off offset:576 nt
	s_nop 0
	global_load_dwordx4 v[216:219], v[158:159], off nt
	global_load_dwordx4 v[220:223], v[158:159], off offset:64 nt
	global_load_dwordx4 v[224:227], v[158:159], off offset:512 nt
	global_load_dwordx4 v[228:231], v[158:159], off offset:576 nt
	v_lshl_add_u64 v[158:159], s[30:31], 0, v[234:235]
	v_lshl_add_u64 v[158:159], v[158:159], 0, v[232:233]
	v_lshl_add_u64 v[234:235], s[30:31], 0, v[236:237]
	v_lshl_add_u64 v[236:237], s[30:31], 0, v[238:239]
	v_lshl_add_u64 v[238:239], s[30:31], 0, v[240:241]
	v_lshl_add_u64 v[234:235], v[234:235], 0, v[232:233]
	v_lshl_add_u64 v[236:237], v[236:237], 0, v[232:233]
	v_lshl_add_u64 v[232:233], v[238:239], 0, v[232:233]
	s_mov_b32 s56, s14
	s_mov_b32 s22, s16
	s_mov_b64 s[26:27], s[20:21]
	s_mov_b64 s[24:25], s[18:19]
	s_waitcnt vmcnt(0)
	v_pk_fma_f32 v[126:127], v[126:127], v[142:143], v[170:171]
	v_pk_fma_f32 v[124:125], v[124:125], v[140:141], v[168:169]
	v_pk_fma_f32 v[122:123], v[122:123], v[138:139], v[174:175]
	v_pk_fma_f32 v[120:121], v[120:121], v[136:137], v[172:173]
	v_pk_fma_f32 v[110:111], v[110:111], v[134:135], v[178:179]
	v_pk_fma_f32 v[108:109], v[108:109], v[132:133], v[176:177]
	v_pk_fma_f32 v[102:103], v[102:103], v[130:131], v[182:183]
	v_pk_fma_f32 v[100:101], v[100:101], v[128:129], v[180:181]
	global_store_dwordx4 v[158:159], v[124:127], off
	global_store_dwordx4 v[158:159], v[120:123], off offset:64
	global_store_dwordx4 v[158:159], v[108:111], off offset:512
	global_store_dwordx4 v[158:159], v[100:103], off offset:576
	v_pk_fma_f32 v[90:91], v[90:91], v[134:135], v[194:195]
	v_pk_fma_f32 v[110:111], v[114:115], v[138:139], v[190:191]
	v_pk_fma_f32 v[102:103], v[118:119], v[142:143], v[186:187]
	v_pk_fma_f32 v[100:101], v[116:117], v[140:141], v[184:185]
	v_pk_fma_f32 v[74:75], v[74:75], v[130:131], v[214:215]
	v_pk_fma_f32 v[72:73], v[72:73], v[128:129], v[212:213]
	v_pk_fma_f32 v[66:67], v[66:67], v[130:131], v[230:231]
	v_pk_fma_f32 v[64:65], v[64:65], v[128:129], v[228:229]
	v_pk_fma_f32 v[108:109], v[112:113], v[136:137], v[188:189]
	v_pk_fma_f32 v[88:89], v[88:89], v[132:133], v[192:193]
	v_pk_fma_f32 v[86:87], v[86:87], v[130:131], v[198:199]
	v_pk_fma_f32 v[84:85], v[84:85], v[128:129], v[196:197]
	v_pk_fma_f32 v[106:107], v[106:107], v[142:143], v[202:203]
	v_pk_fma_f32 v[104:105], v[104:105], v[140:141], v[200:201]
	v_pk_fma_f32 v[98:99], v[98:99], v[138:139], v[206:207]
	v_pk_fma_f32 v[96:97], v[96:97], v[136:137], v[204:205]
	v_pk_fma_f32 v[82:83], v[82:83], v[134:135], v[210:211]
	v_pk_fma_f32 v[80:81], v[80:81], v[132:133], v[208:209]
	v_pk_fma_f32 v[94:95], v[94:95], v[142:143], v[218:219]
	v_pk_fma_f32 v[92:93], v[92:93], v[140:141], v[216:217]
	global_store_dwordx4 v[234:235], v[100:103], off
	global_store_dwordx4 v[234:235], v[108:111], off offset:64
	global_store_dwordx4 v[234:235], v[88:91], off offset:512
	global_store_dwordx4 v[234:235], v[84:87], off offset:576
	global_store_dwordx4 v[236:237], v[104:107], off
	global_store_dwordx4 v[236:237], v[96:99], off offset:64
	global_store_dwordx4 v[236:237], v[80:83], off offset:512
	global_store_dwordx4 v[236:237], v[72:75], off offset:576
	global_store_dwordx4 v[232:233], v[92:95], off
	v_pk_fma_f32 v[70:71], v[70:71], v[134:135], v[226:227]
	v_pk_fma_f32 v[74:75], v[78:79], v[138:139], v[222:223]
	v_pk_fma_f32 v[72:73], v[76:77], v[136:137], v[220:221]
	v_pk_fma_f32 v[68:69], v[68:69], v[132:133], v[224:225]
	global_store_dwordx4 v[232:233], v[64:67], off offset:576
	global_store_dwordx4 v[232:233], v[72:75], off offset:64
	global_store_dwordx4 v[232:233], v[68:71], off offset:512
	v_add_co_u32_e32 v64, vcc, s50, v160
	v_lshl_add_u64 v[80:81], v[160:161], 0, s[6:7]
	s_nop 0
	v_addc_co_u32_e32 v65, vcc, 0, v161, vcc
	global_load_dwordx4 v[64:67], v[64:65], off nt
	s_nop 0
	global_load_dwordx4 v[68:71], v[80:81], off offset:64 nt
	global_load_dwordx4 v[72:75], v[80:81], off offset:512 nt
	global_load_dwordx4 v[76:79], v[80:81], off offset:576 nt
	v_add_co_u32_e32 v80, vcc, s51, v160
	v_lshl_add_u64 v[92:93], v[160:161], 0, s[8:9]
	s_nop 0
	v_addc_co_u32_e32 v81, vcc, 0, v161, vcc
	global_load_dwordx4 v[80:83], v[80:81], off nt
	s_nop 0
	global_load_dwordx4 v[84:87], v[92:93], off offset:64 nt
	global_load_dwordx4 v[88:91], v[92:93], off offset:512 nt
	s_nop 0
	global_load_dwordx4 v[92:95], v[92:93], off offset:576 nt
	v_add_co_u32_e32 v96, vcc, s54, v160
	v_lshl_add_u64 v[108:109], v[160:161], 0, s[10:11]
	s_nop 0
	v_addc_co_u32_e32 v97, vcc, 0, v161, vcc
	global_load_dwordx4 v[96:99], v[96:97], off nt
	s_nop 0
	global_load_dwordx4 v[100:103], v[108:109], off offset:64 nt
	global_load_dwordx4 v[104:107], v[108:109], off offset:512 nt
	s_nop 0
	global_load_dwordx4 v[108:111], v[108:109], off offset:576 nt
	v_add_co_u32_e32 v112, vcc, s55, v160
	v_lshl_add_u64 v[124:125], v[160:161], 0, s[12:13]
	s_nop 0
	v_addc_co_u32_e32 v113, vcc, 0, v161, vcc
	global_load_dwordx4 v[112:115], v[112:113], off nt
	s_nop 0
	global_load_dwordx4 v[116:119], v[124:125], off offset:64 nt
	global_load_dwordx4 v[120:123], v[124:125], off offset:512 nt
	s_nop 0
	global_load_dwordx4 v[124:127], v[124:125], off offset:576 nt
	v_add_co_u32_e32 v168, vcc, s50, v158
	v_lshl_add_u64 v[160:161], v[158:159], 0, s[6:7]
	s_nop 0
	v_addc_co_u32_e32 v169, vcc, 0, v159, vcc
	v_add_co_u32_e32 v172, vcc, s51, v158
	v_lshl_add_u64 v[170:171], v[158:159], 0, s[8:9]
	s_nop 0
	v_addc_co_u32_e32 v173, vcc, 0, v159, vcc
	v_lshl_add_u64 v[174:175], v[158:159], 0, s[10:11]
	s_waitcnt vmcnt(0)
	v_pk_fma_f32 v[62:63], v[62:63], v[142:143], v[66:67]
	v_pk_fma_f32 v[60:61], v[60:61], v[140:141], v[64:65]
	v_pk_fma_f32 v[58:59], v[58:59], v[138:139], v[70:71]
	v_pk_fma_f32 v[56:57], v[56:57], v[136:137], v[68:69]
	v_pk_fma_f32 v[42:43], v[42:43], v[134:135], v[74:75]
	v_pk_fma_f32 v[40:41], v[40:41], v[132:133], v[72:73]
	v_pk_fma_f32 v[38:39], v[38:39], v[130:131], v[78:79]
	v_pk_fma_f32 v[36:37], v[36:37], v[128:129], v[76:77]
	v_pk_fma_f32 v[54:55], v[54:55], v[142:143], v[82:83]
	v_pk_fma_f32 v[28:29], v[28:29], v[128:129], v[92:93]
	v_pk_fma_f32 v[52:53], v[52:53], v[140:141], v[80:81]
	v_pk_fma_f32 v[50:51], v[50:51], v[138:139], v[86:87]
	v_pk_fma_f32 v[48:49], v[48:49], v[136:137], v[84:85]
	v_pk_fma_f32 v[34:35], v[34:35], v[134:135], v[90:91]
	v_pk_fma_f32 v[32:33], v[32:33], v[132:133], v[88:89]
	v_pk_fma_f32 v[30:31], v[30:31], v[130:131], v[94:95]
	global_store_dwordx4 v[168:169], v[60:63], off
	global_store_dwordx4 v[160:161], v[56:59], off offset:64
	global_store_dwordx4 v[160:161], v[40:43], off offset:512
	global_store_dwordx4 v[160:161], v[36:39], off offset:576
	global_store_dwordx4 v[172:173], v[52:55], off
	global_store_dwordx4 v[170:171], v[48:51], off offset:64
	global_store_dwordx4 v[170:171], v[32:35], off offset:512
	global_store_dwordx4 v[170:171], v[28:31], off offset:576
	v_pk_fma_f32 v[18:19], v[18:19], v[134:135], v[106:107]
	v_pk_fma_f32 v[16:17], v[16:17], v[132:133], v[104:105]
	v_add_co_u32_e32 v28, vcc, s54, v158
	global_store_dwordx4 v[174:175], v[16:19], off offset:512
	s_nop 0
	v_addc_co_u32_e32 v29, vcc, 0, v159, vcc
	v_add_co_u32_e32 v18, vcc, s55, v158
	v_pk_fma_f32 v[14:15], v[14:15], v[130:131], v[110:111]
	v_pk_fma_f32 v[12:13], v[12:13], v[128:129], v[108:109]
	v_addc_co_u32_e32 v19, vcc, 0, v159, vcc
	v_pk_fma_f32 v[46:47], v[46:47], v[142:143], v[98:99]
	v_pk_fma_f32 v[44:45], v[44:45], v[140:141], v[96:97]
	v_pk_fma_f32 v[26:27], v[26:27], v[138:139], v[102:103]
	v_pk_fma_f32 v[24:25], v[24:25], v[136:137], v[100:101]
	global_store_dwordx4 v[174:175], v[12:15], off offset:576
	v_lshl_add_u64 v[16:17], v[158:159], 0, s[12:13]
	v_pk_fma_f32 v[10:11], v[10:11], v[138:139], v[118:119]
	v_pk_fma_f32 v[14:15], v[22:23], v[142:143], v[114:115]
	v_pk_fma_f32 v[12:13], v[20:21], v[140:141], v[112:113]
	v_pk_fma_f32 v[8:9], v[8:9], v[136:137], v[116:117]
	v_pk_fma_f32 v[6:7], v[6:7], v[134:135], v[122:123]
	v_pk_fma_f32 v[4:5], v[4:5], v[132:133], v[120:121]
	v_pk_fma_f32 v[2:3], v[2:3], v[130:131], v[126:127]
	v_pk_fma_f32 v[0:1], v[0:1], v[128:129], v[124:125]
	s_and_b64 vcc, exec, s[0:1]
	global_store_dwordx4 v[28:29], v[44:47], off
	global_store_dwordx4 v[174:175], v[24:27], off offset:64
	global_store_dwordx4 v[18:19], v[12:15], off
	global_store_dwordx4 v[16:17], v[8:11], off offset:64
	global_store_dwordx4 v[16:17], v[4:7], off offset:512
	global_store_dwordx4 v[16:17], v[0:3], off offset:576
	s_cbranch_vccz .LBB0_607
	s_waitcnt vmcnt(0)
	s_cmpk_gt_u32 s33, 0xff
	s_cbranch_scc1 .LBB0_618
	s_barrier
